# GEMM K-loops: one static s_setprio 1 for the wave half that arrives second (wr=1), no per-segment toggling
# baseline (speedup 1.0000x reference)
.LBB0_69:
	s_add_i32 m0, s3, 0x18000
	v_lshl_add_u64 v[0:1], v[0:1], 0, s[66:67]
	s_waitcnt vmcnt(4)
	s_barrier
	global_load_lds_dwordx4 v[0:1], off
	v_lshl_add_u64 v[0:1], v[2:3], 0, s[66:67]
	s_add_i32 m0, s3, 0x1a000
	s_add_i32 s30, s3, 0x8000
	global_load_lds_dwordx4 v[0:1], off
	v_lshl_add_u64 v[0:1], v[4:5], 0, s[66:67]
	s_mov_b32 m0, s30
	s_add_i32 s31, s3, 0xa000
	global_load_lds_dwordx4 v[0:1], off
	v_lshl_add_u64 v[0:1], v[6:7], 0, s[66:67]
	s_mov_b32 m0, s31
	v_and_b32_e32 v19, 15, v15
	global_load_lds_dwordx4 v[0:1], off
	s_add_i32 m0, s3, 0x1c000
	v_lshl_add_u64 v[0:1], v[8:9], 0, s[66:67]
	global_load_lds_dwordx4 v[0:1], off
	v_lshl_add_u64 v[0:1], v[10:11], 0, s[66:67]
	s_add_i32 m0, s3, 0x1e000
	v_and_b32_e32 v20, 48, v15
	global_load_lds_dwordx4 v[0:1], off
	v_lshlrev_b32_e32 v19, 6, v19
	v_lshlrev_b32_e32 v15, 2, v15
	s_lshr_b32 s29, s19, 6
	v_or_b32_e32 v21, v19, v20
	s_lshl_b32 s19, s23, 13
	v_and_b32_e32 v15, 32, v15
	v_bitop3_b32 v19, v19, v15, v20 bitop3:0x36
	v_bitop3_b32 v15, v21, s19, v15 bitop3:0xde
	s_lshl_b32 s19, s22, 12
	s_and_b32 s19, s19, 0x3000
	s_add_i32 s34, s29, -2
	s_add_u32 s16, s18, s16
	s_addc_u32 s17, 0, s17
	s_add_u32 s12, s16, s12
	s_addc_u32 s13, s17, s13
	s_add_u32 s12, s12, s25
	s_addc_u32 s13, s13, 0
	s_add_u32 s12, s80, s12
	s_addc_u32 s13, s81, s13
	v_add_u32_e32 v0, v16, v17
	s_add_u32 s12, s12, 0x80
	v_add_lshl_u32 v0, v0, v18, 1
	v_mov_b32_e32 v1, v133
	s_addc_u32 s13, s13, 0
	v_lshl_add_u64 v[130:131], s[12:13], 0, v[0:1]
	v_add_u32_e32 v0, v12, v13
	s_waitcnt vmcnt(6)
	v_add_lshl_u32 v0, v0, v14, 1
	v_lshl_add_u64 v[150:151], s[12:13], 0, v[0:1]
	v_mov_b32_e32 v0, 0
	v_or_b32_e32 v152, s19, v19
	s_mov_b32 s18, 0
	s_mov_b64 s[12:13], 0
	v_add_u32_e32 v153, 0, v15
	v_mov_b32_e32 v1, v0
	v_mov_b64_e32 v[2:3], 0
	v_mov_b64_e32 v[4:5], 0
	v_mov_b64_e32 v[6:7], 0
	v_mov_b64_e32 v[8:9], 0
	v_mov_b64_e32 v[10:11], 0
	v_mov_b64_e32 v[12:13], 0
	v_mov_b64_e32 v[14:15], 0
	v_mov_b64_e32 v[16:17], 0
	v_mov_b64_e32 v[18:19], 0
	v_mov_b64_e32 v[20:21], 0
	v_mov_b64_e32 v[22:23], 0
	v_mov_b64_e32 v[24:25], 0
	v_mov_b64_e32 v[26:27], 0
	v_mov_b64_e32 v[28:29], 0
	v_mov_b64_e32 v[30:31], 0
	v_mov_b64_e32 v[32:33], 0
	v_mov_b64_e32 v[34:35], 0
	v_mov_b64_e32 v[36:37], 0
	v_mov_b64_e32 v[38:39], 0
	v_mov_b64_e32 v[40:41], 0
	v_mov_b64_e32 v[42:43], 0
	v_mov_b64_e32 v[44:45], 0
	v_mov_b64_e32 v[46:47], 0
	v_mov_b64_e32 v[48:49], 0
	v_mov_b64_e32 v[50:51], 0
	v_mov_b64_e32 v[52:53], 0
	v_mov_b64_e32 v[54:55], 0
	v_mov_b64_e32 v[56:57], 0
	v_mov_b64_e32 v[58:59], 0
	v_mov_b64_e32 v[60:61], 0
	v_mov_b64_e32 v[62:63], 0
	v_mov_b64_e32 v[64:65], 0
	v_mov_b64_e32 v[66:67], 0
	v_mov_b64_e32 v[68:69], 0
	v_mov_b64_e32 v[70:71], 0
	v_mov_b64_e32 v[72:73], 0
	v_mov_b64_e32 v[74:75], 0
	v_mov_b64_e32 v[76:77], 0
	v_mov_b64_e32 v[78:79], 0
	v_mov_b64_e32 v[80:81], 0
	v_mov_b64_e32 v[82:83], 0
	v_mov_b64_e32 v[84:85], 0
	v_mov_b64_e32 v[86:87], 0
	v_mov_b64_e32 v[88:89], 0
	v_mov_b64_e32 v[90:91], 0
	v_mov_b64_e32 v[92:93], 0
	v_mov_b64_e32 v[94:95], 0
	v_mov_b64_e32 v[96:97], 0
	v_mov_b64_e32 v[98:99], 0
	v_mov_b64_e32 v[100:101], 0
	v_mov_b64_e32 v[102:103], 0
	v_mov_b64_e32 v[104:105], 0
	v_mov_b64_e32 v[106:107], 0
	v_mov_b64_e32 v[108:109], 0
	v_mov_b64_e32 v[110:111], 0
	v_mov_b64_e32 v[112:113], 0
	v_mov_b64_e32 v[114:115], 0
	v_mov_b64_e32 v[116:117], 0
	v_mov_b64_e32 v[118:119], 0
	v_mov_b64_e32 v[120:121], 0
	v_mov_b64_e32 v[122:123], 0
	v_mov_b64_e32 v[124:125], 0
	v_mov_b64_e32 v[126:127], 0
	s_barrier
	v_add_u32_e32 v166, 0x10000, v152
	ds_read_b128 v[154:157], v166
	ds_read_b128 v[158:161], v166 offset:1024
	ds_read_b128 v[162:165], v166 offset:2048
	ds_read_b128 v[166:169], v166 offset:3072
	v_readfirstlane_b32 s98, v135
	s_cmpk_gt_u32 s98, 0xff
	s_cbranch_scc0 .Lkprio_0
	s_setprio 1
.Lkprio_0:
.LBB0_70:
	s_add_i32 s35, s18, 2
	s_add_u32 s16, s12, 0x100
	s_addc_u32 s17, s13, 0
	s_cmp_lg_u32 s34, s18
	s_cselect_b32 s22, s16, 0
	s_cselect_b32 s23, s17, 0
	s_add_u32 s18, s10, s22
	s_addc_u32 s19, s11, s23
	s_add_i32 s36, 0, 0x10000
	s_add_u32 s22, s8, s22
	s_addc_u32 s23, s9, s23
	v_lshl_add_u64 v[190:191], v[130:131], 0, s[12:13]
	s_add_i32 m0, s3, 0xc000
	ds_read_b128 v[170:173], v153
	ds_read_b128 v[178:181], v153 offset:2048
	ds_read_b128 v[186:189], v153 offset:4096
	ds_read_b128 v[220:223], v153 offset:6144
	ds_read_b128 v[174:177], v153 offset:1024
	ds_read_b128 v[182:185], v153 offset:3072
	ds_read_b128 v[216:219], v153 offset:5120
	ds_read_b128 v[224:227], v153 offset:7168
	global_load_lds_dwordx4 v[190:191], off
	v_lshl_add_u64 v[190:191], v[150:151], 0, s[12:13]
	s_add_i32 m0, s3, 0xe000
	s_nop 0
	global_load_lds_dwordx4 v[190:191], off
	s_waitcnt lgkmcnt(8)
	s_waitcnt vmcnt(10)
	s_barrier
	s_waitcnt lgkmcnt(4)
	v_mfma_f32_16x16x32_bf16 v[124:127], v[154:157], v[170:173], v[124:127]
	v_mfma_f32_16x16x32_bf16 v[120:123], v[162:165], v[170:173], v[120:123]
	v_mfma_f32_16x16x32_bf16 v[116:119], v[154:157], v[178:181], v[116:119]
	v_mfma_f32_16x16x32_bf16 v[108:111], v[162:165], v[178:181], v[108:111]
	v_mfma_f32_16x16x32_bf16 v[100:103], v[154:157], v[186:189], v[100:103]
	v_mfma_f32_16x16x32_bf16 v[92:95], v[162:165], v[186:189], v[92:95]
	v_mfma_f32_16x16x32_bf16 v[84:87], v[154:157], v[220:223], v[84:87]
	v_mfma_f32_16x16x32_bf16 v[76:79], v[162:165], v[220:223], v[76:79]
	s_waitcnt lgkmcnt(0)
	v_mfma_f32_16x16x32_bf16 v[124:127], v[158:161], v[174:177], v[124:127]
	v_mfma_f32_16x16x32_bf16 v[120:123], v[166:169], v[174:177], v[120:123]
	v_mfma_f32_16x16x32_bf16 v[116:119], v[158:161], v[182:185], v[116:119]
	v_mfma_f32_16x16x32_bf16 v[108:111], v[166:169], v[182:185], v[108:111]
	v_mfma_f32_16x16x32_bf16 v[100:103], v[158:161], v[216:219], v[100:103]
	v_mfma_f32_16x16x32_bf16 v[92:95], v[166:169], v[216:219], v[92:95]
	v_mfma_f32_16x16x32_bf16 v[84:87], v[158:161], v[224:227], v[84:87]
	v_mfma_f32_16x16x32_bf16 v[76:79], v[166:169], v[224:227], v[76:79]
	s_barrier
	s_add_i32 s37, 0, 0x14000
	v_add_u32_e32 v190, s37, v152
	s_add_i32 s12, s36, s26
	ds_read_b128 v[228:231], v190
	ds_read_b128 v[236:239], v190 offset:2048
	ds_read_b128 v[232:235], v190 offset:1024
	ds_read_b128 v[240:243], v190 offset:3072
	v_lshl_add_u64 v[190:191], s[22:23], 0, v[132:133]
	s_mov_b32 m0, s12
	v_lshl_add_u64 v[244:245], s[22:23], 0, v[128:129]
	global_load_lds_dwordx4 v132, s[22:23]
	s_add_i32 m0, s12, 0x2000
	s_nop 0
	global_load_lds_dwordx4 v128, s[22:23]
	s_waitcnt vmcnt(10)
	s_barrier
	s_waitcnt lgkmcnt(2)
	v_mfma_f32_16x16x32_bf16 v[112:115], v[228:231], v[170:173], v[112:115]
	v_mfma_f32_16x16x32_bf16 v[104:107], v[236:239], v[170:173], v[104:107]
	v_mfma_f32_16x16x32_bf16 v[96:99], v[228:231], v[178:181], v[96:99]
	v_mfma_f32_16x16x32_bf16 v[88:91], v[236:239], v[178:181], v[88:91]
	v_mfma_f32_16x16x32_bf16 v[80:83], v[228:231], v[186:189], v[80:83]
	v_mfma_f32_16x16x32_bf16 v[72:75], v[236:239], v[186:189], v[72:75]
	v_mfma_f32_16x16x32_bf16 v[68:71], v[228:231], v[220:223], v[68:71]
	v_mfma_f32_16x16x32_bf16 v[64:67], v[236:239], v[220:223], v[64:67]
	s_waitcnt lgkmcnt(0)
	v_mfma_f32_16x16x32_bf16 v[112:115], v[232:235], v[174:177], v[112:115]
	v_mfma_f32_16x16x32_bf16 v[104:107], v[240:243], v[174:177], v[104:107]
	v_mfma_f32_16x16x32_bf16 v[96:99], v[232:235], v[182:185], v[96:99]
	v_mfma_f32_16x16x32_bf16 v[88:91], v[240:243], v[182:185], v[88:91]
	v_mfma_f32_16x16x32_bf16 v[80:83], v[232:235], v[216:219], v[80:83]
	v_mfma_f32_16x16x32_bf16 v[72:75], v[240:243], v[216:219], v[72:75]
	v_mfma_f32_16x16x32_bf16 v[68:71], v[232:235], v[224:227], v[68:71]
	v_mfma_f32_16x16x32_bf16 v[64:67], v[240:243], v[224:227], v[64:67]
	s_mov_b32 m0, s3
	s_barrier
	ds_read_b128 v[170:173], v153 offset:16384
	ds_read_b128 v[178:181], v153 offset:18432
	ds_read_b128 v[186:189], v153 offset:20480
	ds_read_b128 v[220:223], v153 offset:22528
	ds_read_b128 v[174:177], v153 offset:17408
	ds_read_b128 v[182:185], v153 offset:19456
	ds_read_b128 v[216:219], v153 offset:21504
	ds_read_b128 v[224:227], v153 offset:23552
	global_load_lds_dwordx4 v132, s[18:19]
	s_mov_b32 m0, s5
	s_nop 0
	global_load_lds_dwordx4 v128, s[18:19]
	s_waitcnt vmcnt(10)
	s_barrier
	s_waitcnt lgkmcnt(4)
	v_mfma_f32_16x16x32_bf16 v[60:63], v[154:157], v[170:173], v[60:63]
	v_mfma_f32_16x16x32_bf16 v[56:59], v[162:165], v[170:173], v[56:59]
	v_mfma_f32_16x16x32_bf16 v[52:55], v[154:157], v[178:181], v[52:55]
	v_mfma_f32_16x16x32_bf16 v[44:47], v[162:165], v[178:181], v[44:47]
	v_mfma_f32_16x16x32_bf16 v[36:39], v[154:157], v[186:189], v[36:39]
	v_mfma_f32_16x16x32_bf16 v[28:31], v[162:165], v[186:189], v[28:31]
	v_mfma_f32_16x16x32_bf16 v[20:23], v[154:157], v[220:223], v[20:23]
	v_mfma_f32_16x16x32_bf16 v[12:15], v[162:165], v[220:223], v[12:15]
	s_waitcnt lgkmcnt(0)
	v_mfma_f32_16x16x32_bf16 v[60:63], v[158:161], v[174:177], v[60:63]
	v_mfma_f32_16x16x32_bf16 v[56:59], v[166:169], v[174:177], v[56:59]
	v_mfma_f32_16x16x32_bf16 v[52:55], v[158:161], v[182:185], v[52:55]
	v_mfma_f32_16x16x32_bf16 v[44:47], v[166:169], v[182:185], v[44:47]
	v_mfma_f32_16x16x32_bf16 v[36:39], v[158:161], v[216:219], v[36:39]
	v_mfma_f32_16x16x32_bf16 v[28:31], v[166:169], v[216:219], v[28:31]
	v_mfma_f32_16x16x32_bf16 v[20:23], v[158:161], v[224:227], v[20:23]
	v_mfma_f32_16x16x32_bf16 v[12:15], v[166:169], v[224:227], v[12:15]
	s_barrier
	s_add_u32 s12, s22, s25
	s_addc_u32 s13, s23, 0
	s_add_i32 s22, s37, s26
	v_lshl_add_u64 v[250:251], s[12:13], 0, v[132:133]
	s_mov_b32 m0, s22
	v_lshl_add_u64 v[252:253], s[12:13], 0, v[128:129]
	global_load_lds_dwordx4 v132, s[12:13]
	s_add_i32 m0, s22, 0x2000
	s_nop 0
	global_load_lds_dwordx4 v128, s[12:13]
	v_add_u32_e32 v166, 0x18000, v152
	ds_read_b128 v[154:157], v166
	ds_read_b128 v[158:161], v166 offset:1024
	ds_read_b128 v[162:165], v166 offset:2048
	ds_read_b128 v[166:169], v166 offset:3072
	s_waitcnt vmcnt(10)
	s_barrier
	v_mfma_f32_16x16x32_bf16 v[48:51], v[228:231], v[170:173], v[48:51]
	v_mfma_f32_16x16x32_bf16 v[40:43], v[236:239], v[170:173], v[40:43]
	v_mfma_f32_16x16x32_bf16 v[32:35], v[228:231], v[178:181], v[32:35]
	v_mfma_f32_16x16x32_bf16 v[24:27], v[236:239], v[178:181], v[24:27]
	v_mfma_f32_16x16x32_bf16 v[16:19], v[228:231], v[186:189], v[16:19]
	v_mfma_f32_16x16x32_bf16 v[8:11], v[236:239], v[186:189], v[8:11]
	v_mfma_f32_16x16x32_bf16 v[4:7], v[228:231], v[220:223], v[4:7]
	v_mfma_f32_16x16x32_bf16 v[0:3], v[236:239], v[220:223], v[0:3]
	v_mfma_f32_16x16x32_bf16 v[48:51], v[232:235], v[174:177], v[48:51]
	v_mfma_f32_16x16x32_bf16 v[40:43], v[240:243], v[174:177], v[40:43]
	v_mfma_f32_16x16x32_bf16 v[32:35], v[232:235], v[182:185], v[32:35]
	v_mfma_f32_16x16x32_bf16 v[24:27], v[240:243], v[182:185], v[24:27]
	v_mfma_f32_16x16x32_bf16 v[16:19], v[232:235], v[216:219], v[16:19]
	v_mfma_f32_16x16x32_bf16 v[8:11], v[240:243], v[216:219], v[8:11]
	v_mfma_f32_16x16x32_bf16 v[4:7], v[232:235], v[224:227], v[4:7]
	v_mfma_f32_16x16x32_bf16 v[0:3], v[240:243], v[224:227], v[0:3]
	s_add_i32 s22, 0, 0x18000
	s_barrier
	s_add_u32 s12, s18, s25
	s_addc_u32 s13, s19, 0
	s_mov_b32 m0, s27
	ds_read_b128 v[170:173], v153 offset:32768
	ds_read_b128 v[178:181], v153 offset:34816
	ds_read_b128 v[186:189], v153 offset:36864
	ds_read_b128 v[220:223], v153 offset:38912
	ds_read_b128 v[174:177], v153 offset:33792
	ds_read_b128 v[182:185], v153 offset:35840
	ds_read_b128 v[216:219], v153 offset:37888
	ds_read_b128 v[224:227], v153 offset:39936
	global_load_lds_dwordx4 v132, s[12:13]
	s_mov_b32 m0, s28
	s_nop 0
	global_load_lds_dwordx4 v128, s[12:13]
	s_waitcnt lgkmcnt(8)
	s_waitcnt vmcnt(10)
	s_barrier
	s_waitcnt lgkmcnt(4)
	v_mfma_f32_16x16x32_bf16 v[124:127], v[154:157], v[170:173], v[124:127]
	v_mfma_f32_16x16x32_bf16 v[120:123], v[162:165], v[170:173], v[120:123]
	v_mfma_f32_16x16x32_bf16 v[116:119], v[154:157], v[178:181], v[116:119]
	v_mfma_f32_16x16x32_bf16 v[108:111], v[162:165], v[178:181], v[108:111]
	v_mfma_f32_16x16x32_bf16 v[100:103], v[154:157], v[186:189], v[100:103]
	v_mfma_f32_16x16x32_bf16 v[92:95], v[162:165], v[186:189], v[92:95]
	v_mfma_f32_16x16x32_bf16 v[84:87], v[154:157], v[220:223], v[84:87]
	v_mfma_f32_16x16x32_bf16 v[76:79], v[162:165], v[220:223], v[76:79]
	s_waitcnt lgkmcnt(0)
	v_mfma_f32_16x16x32_bf16 v[124:127], v[158:161], v[174:177], v[124:127]
	v_mfma_f32_16x16x32_bf16 v[120:123], v[166:169], v[174:177], v[120:123]
	v_mfma_f32_16x16x32_bf16 v[116:119], v[158:161], v[182:185], v[116:119]
	v_mfma_f32_16x16x32_bf16 v[108:111], v[166:169], v[182:185], v[108:111]
	v_mfma_f32_16x16x32_bf16 v[100:103], v[158:161], v[216:219], v[100:103]
	v_mfma_f32_16x16x32_bf16 v[92:95], v[166:169], v[216:219], v[92:95]
	v_mfma_f32_16x16x32_bf16 v[84:87], v[158:161], v[224:227], v[84:87]
	v_mfma_f32_16x16x32_bf16 v[76:79], v[166:169], v[224:227], v[76:79]
	s_barrier
	s_add_i32 s12, 0, 0x1c000
	s_add_i32 s13, s22, s26
	v_add_u32_e32 v200, s12, v152
	v_lshl_add_u64 v[190:191], v[190:191], 0, s[66:67]
	s_mov_b32 m0, s13
	ds_read_b128 v[228:231], v200
	ds_read_b128 v[236:239], v200 offset:2048
	ds_read_b128 v[232:235], v200 offset:1024
	ds_read_b128 v[240:243], v200 offset:3072
	global_load_lds_dwordx4 v[190:191], off
	v_lshl_add_u64 v[190:191], v[244:245], 0, s[66:67]
	s_add_i32 m0, s13, 0x2000
	s_nop 0
	global_load_lds_dwordx4 v[190:191], off
	s_waitcnt vmcnt(10)
	s_barrier
	s_waitcnt lgkmcnt(2)
	v_mfma_f32_16x16x32_bf16 v[112:115], v[228:231], v[170:173], v[112:115]
	v_mfma_f32_16x16x32_bf16 v[104:107], v[236:239], v[170:173], v[104:107]
	v_mfma_f32_16x16x32_bf16 v[96:99], v[228:231], v[178:181], v[96:99]
	v_mfma_f32_16x16x32_bf16 v[88:91], v[236:239], v[178:181], v[88:91]
	v_mfma_f32_16x16x32_bf16 v[80:83], v[228:231], v[186:189], v[80:83]
	v_mfma_f32_16x16x32_bf16 v[72:75], v[236:239], v[186:189], v[72:75]
	v_mfma_f32_16x16x32_bf16 v[68:71], v[228:231], v[220:223], v[68:71]
	v_mfma_f32_16x16x32_bf16 v[64:67], v[236:239], v[220:223], v[64:67]
	s_waitcnt lgkmcnt(0)
	v_mfma_f32_16x16x32_bf16 v[112:115], v[232:235], v[174:177], v[112:115]
	v_mfma_f32_16x16x32_bf16 v[104:107], v[240:243], v[174:177], v[104:107]
	v_mfma_f32_16x16x32_bf16 v[96:99], v[232:235], v[182:185], v[96:99]
	v_mfma_f32_16x16x32_bf16 v[88:91], v[240:243], v[182:185], v[88:91]
	v_mfma_f32_16x16x32_bf16 v[80:83], v[232:235], v[216:219], v[80:83]
	v_mfma_f32_16x16x32_bf16 v[72:75], v[240:243], v[216:219], v[72:75]
	v_mfma_f32_16x16x32_bf16 v[68:71], v[232:235], v[224:227], v[68:71]
	v_mfma_f32_16x16x32_bf16 v[64:67], v[240:243], v[224:227], v[64:67]
	s_mov_b32 m0, s30
	s_barrier
	ds_read_b128 v[170:173], v153 offset:49152
	ds_read_b128 v[178:181], v153 offset:51200
	ds_read_b128 v[186:189], v153 offset:53248
	ds_read_b128 v[220:223], v153 offset:55296
	ds_read_b128 v[174:177], v153 offset:50176
	ds_read_b128 v[182:185], v153 offset:52224
	ds_read_b128 v[216:219], v153 offset:54272
	ds_read_b128 v[224:227], v153 offset:56320
	s_add_u32 s98, s18, 0x80
	s_addc_u32 s99, s19, 0
	global_load_lds_dwordx4 v132, s[98:99]
	s_mov_b32 m0, s31
	s_nop 0
	global_load_lds_dwordx4 v128, s[98:99]
	s_waitcnt vmcnt(10)
	s_barrier
	s_waitcnt lgkmcnt(4)
	v_mfma_f32_16x16x32_bf16 v[60:63], v[154:157], v[170:173], v[60:63]
	v_mfma_f32_16x16x32_bf16 v[56:59], v[162:165], v[170:173], v[56:59]
	v_mfma_f32_16x16x32_bf16 v[52:55], v[154:157], v[178:181], v[52:55]
	v_mfma_f32_16x16x32_bf16 v[44:47], v[162:165], v[178:181], v[44:47]
	v_mfma_f32_16x16x32_bf16 v[36:39], v[154:157], v[186:189], v[36:39]
	v_mfma_f32_16x16x32_bf16 v[28:31], v[162:165], v[186:189], v[28:31]
	v_mfma_f32_16x16x32_bf16 v[20:23], v[154:157], v[220:223], v[20:23]
	v_mfma_f32_16x16x32_bf16 v[12:15], v[162:165], v[220:223], v[12:15]
	s_waitcnt lgkmcnt(0)
	v_mfma_f32_16x16x32_bf16 v[60:63], v[158:161], v[174:177], v[60:63]
	v_mfma_f32_16x16x32_bf16 v[56:59], v[166:169], v[174:177], v[56:59]
	v_mfma_f32_16x16x32_bf16 v[52:55], v[158:161], v[182:185], v[52:55]
	v_mfma_f32_16x16x32_bf16 v[44:47], v[166:169], v[182:185], v[44:47]
	v_mfma_f32_16x16x32_bf16 v[36:39], v[158:161], v[216:219], v[36:39]
	v_mfma_f32_16x16x32_bf16 v[28:31], v[166:169], v[216:219], v[28:31]
	v_mfma_f32_16x16x32_bf16 v[20:23], v[158:161], v[224:227], v[20:23]
	v_mfma_f32_16x16x32_bf16 v[12:15], v[166:169], v[224:227], v[12:15]
	s_barrier
	s_add_i32 s12, s12, s26
	v_lshl_add_u64 v[154:155], v[250:251], 0, s[66:67]
	s_mov_b32 m0, s12
	s_nop 0
	global_load_lds_dwordx4 v[154:155], off
	v_lshl_add_u64 v[154:155], v[252:253], 0, s[66:67]
	s_add_i32 m0, s12, 0x2000
	s_nop 0
	global_load_lds_dwordx4 v[154:155], off
	v_add_u32_e32 v166, 0x10000, v152
	ds_read_b128 v[154:157], v166
	ds_read_b128 v[158:161], v166 offset:1024
	ds_read_b128 v[162:165], v166 offset:2048
	ds_read_b128 v[166:169], v166 offset:3072
	s_waitcnt vmcnt(10)
	s_barrier
	v_mfma_f32_16x16x32_bf16 v[48:51], v[228:231], v[170:173], v[48:51]
	v_mfma_f32_16x16x32_bf16 v[40:43], v[236:239], v[170:173], v[40:43]
	v_mfma_f32_16x16x32_bf16 v[32:35], v[228:231], v[178:181], v[32:35]
	v_mfma_f32_16x16x32_bf16 v[24:27], v[236:239], v[178:181], v[24:27]
	v_mfma_f32_16x16x32_bf16 v[16:19], v[228:231], v[186:189], v[16:19]
	v_mfma_f32_16x16x32_bf16 v[8:11], v[236:239], v[186:189], v[8:11]
	v_mfma_f32_16x16x32_bf16 v[4:7], v[228:231], v[220:223], v[4:7]
	v_mfma_f32_16x16x32_bf16 v[0:3], v[236:239], v[220:223], v[0:3]
	v_mfma_f32_16x16x32_bf16 v[48:51], v[232:235], v[174:177], v[48:51]
	v_mfma_f32_16x16x32_bf16 v[40:43], v[240:243], v[174:177], v[40:43]
	v_mfma_f32_16x16x32_bf16 v[32:35], v[232:235], v[182:185], v[32:35]
	v_mfma_f32_16x16x32_bf16 v[24:27], v[240:243], v[182:185], v[24:27]
	v_mfma_f32_16x16x32_bf16 v[16:19], v[232:235], v[216:219], v[16:19]
	v_mfma_f32_16x16x32_bf16 v[8:11], v[240:243], v[216:219], v[8:11]
	v_mfma_f32_16x16x32_bf16 v[4:7], v[232:235], v[224:227], v[4:7]
	v_mfma_f32_16x16x32_bf16 v[0:3], v[240:243], v[224:227], v[0:3]
	s_cmp_ge_u32 s35, s29
	s_mov_b64 s[12:13], s[16:17]
	s_mov_b32 s18, s35
	s_barrier
	s_cbranch_scc0 .LBB0_70
	s_setprio 0
	s_waitcnt lgkmcnt(0)
	s_and_b64 s[6:7], s[6:7], exec
	v_mov_b32_e32 v128, v135
	s_mov_b64 s[6:7], s[0:1]
	s_load_dwordx2 s[6:7], s[6:7], 0x88
	s_cselect_b32 s3, 0x2000, 0
	v_readfirstlane_b32 s5, v128
	v_lshrrev_b32_e32 v129, 2, v128
	v_cvt_pk_bf16_f32 v104, v104, v105
	s_waitcnt lgkmcnt(0)
	s_add_u32 s6, s6, 0xfea4400
	s_addc_u32 s7, s7, 0
	s_ashr_i32 s8, s5, 2
	s_andn2_b32 s8, s8, 63
	v_and_or_b32 v128, v128, 15, s8
	s_lshr_b32 s5, s5, 1
	v_lshl_add_u32 v150, s2, 8, v128
	s_lshl_b32 s2, s4, s15
	s_and_b32 s5, s5, 0x60
	s_add_i32 s2, s2, s3
	v_and_or_b32 v132, v129, 12, s5
	v_add_u32_e32 v130, s2, v150
	v_mov_b64_e32 v[128:129], s[6:7]
	v_mad_i64_i32 v[130:131], s[4:5], v130, s96, v[128:129]
	s_lshl_b32 s58, s58, 9
	v_lshl_add_u64 v[130:131], v[130:131], 0, s[58:59]
	v_lshlrev_b32_e32 v132, 1, v132
	v_lshl_add_u64 v[130:131], v[130:131], 0, v[132:133]
	v_cvt_pk_bf16_f32 v105, v106, v107
	global_store_dwordx2 v[130:131], v[104:105], off offset:1824
	v_add3_u32 v104, s2, 16, v150
	v_mad_i64_i32 v[104:105], s[4:5], v104, s96, v[128:129]
	v_lshl_add_u64 v[104:105], v[104:105], 0, s[58:59]
	v_lshl_add_u64 v[104:105], v[104:105], 0, v[132:133]
	v_cvt_pk_bf16_f32 v88, v88, v89
	v_cvt_pk_bf16_f32 v89, v90, v91
	global_store_dwordx2 v[104:105], v[88:89], off offset:1824
	v_add3_u32 v88, s2, 32, v150
	v_mad_i64_i32 v[88:89], s[4:5], v88, s96, v[128:129]
	v_lshl_add_u64 v[88:89], v[88:89], 0, s[58:59]
	v_lshl_add_u64 v[88:89], v[88:89], 0, v[132:133]
	v_cvt_pk_bf16_f32 v72, v72, v73
	v_cvt_pk_bf16_f32 v73, v74, v75
	global_store_dwordx2 v[88:89], v[72:73], off offset:1824
	v_add3_u32 v72, s2, 48, v150
	v_mad_i64_i32 v[72:73], s[4:5], v72, s96, v[128:129]
	v_lshl_add_u64 v[72:73], v[72:73], 0, s[58:59]
	v_lshl_add_u64 v[72:73], v[72:73], 0, v[132:133]
	v_cvt_pk_bf16_f32 v64, v64, v65
	s_add_i32 s3, s2, 0x80
	v_cvt_pk_bf16_f32 v65, v66, v67
	global_store_dwordx2 v[72:73], v[64:65], off offset:1824
	v_add_u32_e32 v64, s3, v150
	v_mad_i64_i32 v[64:65], s[4:5], v64, s96, v[128:129]
	v_lshl_add_u64 v[64:65], v[64:65], 0, s[58:59]
	v_lshl_add_u64 v[64:65], v[64:65], 0, v[132:133]
	v_cvt_pk_bf16_f32 v40, v40, v41
	s_add_i32 s3, s2, 0x90
	v_cvt_pk_bf16_f32 v41, v42, v43
	global_store_dwordx2 v[64:65], v[40:41], off offset:1824
	v_add_u32_e32 v40, s3, v150
	v_mad_i64_i32 v[40:41], s[4:5], v40, s96, v[128:129]
	v_lshl_add_u64 v[40:41], v[40:41], 0, s[58:59]
	v_lshl_add_u64 v[40:41], v[40:41], 0, v[132:133]
	v_cvt_pk_bf16_f32 v24, v24, v25
	s_add_i32 s3, s2, 0xa0
	v_cvt_pk_bf16_f32 v25, v26, v27
	global_store_dwordx2 v[40:41], v[24:25], off offset:1824
	v_add_u32_e32 v24, s3, v150
	v_mad_i64_i32 v[24:25], s[4:5], v24, s96, v[128:129]
	v_lshl_add_u64 v[24:25], v[24:25], 0, s[58:59]
	v_lshl_add_u64 v[24:25], v[24:25], 0, v[132:133]
	v_cvt_pk_bf16_f32 v8, v8, v9
	s_addk_i32 s2, 0xb0
	v_cvt_pk_bf16_f32 v9, v10, v11
	global_store_dwordx2 v[24:25], v[8:9], off offset:1824
	v_add_u32_e32 v8, s2, v150
	v_mad_i64_i32 v[8:9], s[2:3], v8, s96, v[128:129]
	v_lshl_add_u64 v[8:9], v[8:9], 0, s[58:59]
	v_cvt_pk_bf16_f32 v106, v116, v117
	v_cvt_pk_bf16_f32 v107, v118, v119
	v_cvt_pk_bf16_f32 v90, v100, v101
	v_cvt_pk_bf16_f32 v91, v102, v103
	v_cvt_pk_bf16_f32 v74, v84, v85
	v_cvt_pk_bf16_f32 v75, v86, v87
	v_cvt_pk_bf16_f32 v42, v52, v53
	v_cvt_pk_bf16_f32 v43, v54, v55
	v_cvt_pk_bf16_f32 v26, v36, v37
	v_cvt_pk_bf16_f32 v27, v38, v39
	v_lshl_add_u64 v[8:9], v[8:9], 0, v[132:133]
	v_cvt_pk_bf16_f32 v10, v20, v21
	v_cvt_pk_bf16_f32 v11, v22, v23
	v_cvt_pk_bf16_f32 v124, v124, v125
	v_cvt_pk_bf16_f32 v125, v126, v127
	global_store_dwordx2 v[130:131], v[124:125], off offset:1536
	v_cvt_pk_bf16_f32 v120, v120, v121
	v_cvt_pk_bf16_f32 v121, v122, v123
	global_store_dwordx2 v[130:131], v[120:121], off offset:1568
	v_cvt_pk_bf16_f32 v112, v112, v113
	v_cvt_pk_bf16_f32 v113, v114, v115
	global_store_dwordx2 v[130:131], v[112:113], off offset:1792
	global_store_dwordx2 v[104:105], v[106:107], off offset:1536
	v_cvt_pk_bf16_f32 v106, v108, v109
	v_cvt_pk_bf16_f32 v107, v110, v111
	global_store_dwordx2 v[104:105], v[106:107], off offset:1568
	v_cvt_pk_bf16_f32 v96, v96, v97
	v_cvt_pk_bf16_f32 v97, v98, v99
	global_store_dwordx2 v[104:105], v[96:97], off offset:1792
	global_store_dwordx2 v[88:89], v[90:91], off offset:1536
	v_cvt_pk_bf16_f32 v90, v92, v93
	v_cvt_pk_bf16_f32 v91, v94, v95
	global_store_dwordx2 v[88:89], v[90:91], off offset:1568
	v_cvt_pk_bf16_f32 v80, v80, v81
	v_cvt_pk_bf16_f32 v81, v82, v83
	global_store_dwordx2 v[88:89], v[80:81], off offset:1792
	global_store_dwordx2 v[72:73], v[74:75], off offset:1536
	v_cvt_pk_bf16_f32 v74, v76, v77
	v_cvt_pk_bf16_f32 v75, v78, v79
	global_store_dwordx2 v[72:73], v[74:75], off offset:1568
	v_cvt_pk_bf16_f32 v68, v68, v69
	v_cvt_pk_bf16_f32 v69, v70, v71
	global_store_dwordx2 v[72:73], v[68:69], off offset:1792
	v_cvt_pk_bf16_f32 v60, v60, v61
	v_cvt_pk_bf16_f32 v61, v62, v63
	global_store_dwordx2 v[64:65], v[60:61], off offset:1536
	v_cvt_pk_bf16_f32 v56, v56, v57
	v_cvt_pk_bf16_f32 v57, v58, v59
	global_store_dwordx2 v[64:65], v[56:57], off offset:1568
	v_cvt_pk_bf16_f32 v48, v48, v49
	v_cvt_pk_bf16_f32 v49, v50, v51
	global_store_dwordx2 v[64:65], v[48:49], off offset:1792
	global_store_dwordx2 v[40:41], v[42:43], off offset:1536
	v_cvt_pk_bf16_f32 v42, v44, v45
	v_cvt_pk_bf16_f32 v43, v46, v47
	global_store_dwordx2 v[40:41], v[42:43], off offset:1568
	v_cvt_pk_bf16_f32 v32, v32, v33
	v_cvt_pk_bf16_f32 v33, v34, v35
	global_store_dwordx2 v[40:41], v[32:33], off offset:1792
	global_store_dwordx2 v[24:25], v[26:27], off offset:1536
	v_cvt_pk_bf16_f32 v26, v28, v29
	v_cvt_pk_bf16_f32 v27, v30, v31
	global_store_dwordx2 v[24:25], v[26:27], off offset:1568
	v_cvt_pk_bf16_f32 v16, v16, v17
	v_cvt_pk_bf16_f32 v17, v18, v19
	global_store_dwordx2 v[24:25], v[16:17], off offset:1792
	global_store_dwordx2 v[8:9], v[10:11], off offset:1536
	v_cvt_pk_bf16_f32 v10, v12, v13
	v_cvt_pk_bf16_f32 v11, v14, v15
	global_store_dwordx2 v[8:9], v[10:11], off offset:1568
	v_cvt_pk_bf16_f32 v4, v4, v5
	v_cvt_pk_bf16_f32 v5, v6, v7
	global_store_dwordx2 v[8:9], v[4:5], off offset:1792
	v_cvt_pk_bf16_f32 v0, v0, v1
	v_cvt_pk_bf16_f32 v1, v2, v3
	global_store_dwordx2 v[8:9], v[0:1], off offset:1824
	s_waitcnt vmcnt(0)
	s_cmpk_lt_u32 s14, 0x100
	s_cbranch_scc0 .LBB0_73
	s_barrier

.LBB0_144:
	s_ashr_i32 s19, s18, 31
	v_cmp_lt_i64_e32 vcc, s[10:11], v[140:141]
	s_lshl_b64 s[10:11], s[18:19], 19
	s_add_u32 s22, s86, s10
	s_addc_u32 s23, s87, s11
	s_and_b64 s[10:11], vcc, exec
	s_cselect_b32 s9, s23, s3
	s_cselect_b32 s12, s22, s2
	s_cmp_eq_u32 s16, 5
	s_cselect_b32 s17, 7, s16
	s_cmp_eq_u32 s16, 7
	s_cselect_b32 s16, 5, s17
	s_ashr_i32 s17, s16, 31
	s_lshl_b64 s[10:11], s[16:17], 19
	s_add_u32 s24, s41, s10
	s_addc_u32 s25, s14, s11
	s_and_b64 s[10:11], vcc, exec
	s_cselect_b32 s13, s25, s7
	s_cselect_b32 s17, s24, s6
	s_add_u32 s2, s2, 0x40080
	s_addc_u32 s3, s3, 0
	s_add_u32 s19, s6, 0x100
	v_mov_b32_e32 v0, 0
	s_addc_u32 s27, s7, 0
	s_waitcnt lgkmcnt(0)
	s_mov_b32 s28, -2
	v_mov_b32_e32 v1, v0
	v_mov_b64_e32 v[2:3], 0
	v_mov_b64_e32 v[4:5], 0
	v_mov_b64_e32 v[6:7], 0
	v_mov_b64_e32 v[8:9], 0
	v_mov_b64_e32 v[10:11], 0
	v_mov_b64_e32 v[12:13], 0
	v_mov_b64_e32 v[14:15], 0
	v_mov_b64_e32 v[16:17], 0
	v_mov_b64_e32 v[18:19], 0
	v_mov_b64_e32 v[20:21], 0
	v_mov_b64_e32 v[22:23], 0
	v_mov_b64_e32 v[24:25], 0
	v_mov_b64_e32 v[26:27], 0
	v_mov_b64_e32 v[28:29], 0
	v_mov_b64_e32 v[30:31], 0
	v_mov_b64_e32 v[32:33], 0
	v_mov_b64_e32 v[34:35], 0
	v_mov_b64_e32 v[36:37], 0
	v_mov_b64_e32 v[38:39], 0
	v_mov_b64_e32 v[40:41], 0
	v_mov_b64_e32 v[42:43], 0
	v_mov_b64_e32 v[44:45], 0
	v_mov_b64_e32 v[46:47], 0
	v_mov_b64_e32 v[48:49], 0
	v_mov_b64_e32 v[50:51], 0
	v_mov_b64_e32 v[52:53], 0
	v_mov_b64_e32 v[54:55], 0
	v_mov_b64_e32 v[56:57], 0
	v_mov_b64_e32 v[58:59], 0
	v_mov_b64_e32 v[60:61], 0
	v_mov_b64_e32 v[62:63], 0
	v_mov_b64_e32 v[64:65], 0
	v_mov_b64_e32 v[66:67], 0
	v_mov_b64_e32 v[68:69], 0
	v_mov_b64_e32 v[70:71], 0
	v_mov_b64_e32 v[72:73], 0
	v_mov_b64_e32 v[74:75], 0
	v_mov_b64_e32 v[76:77], 0
	v_mov_b64_e32 v[78:79], 0
	v_mov_b64_e32 v[80:81], 0
	v_mov_b64_e32 v[82:83], 0
	v_mov_b64_e32 v[84:85], 0
	v_mov_b64_e32 v[86:87], 0
	v_mov_b64_e32 v[88:89], 0
	v_mov_b64_e32 v[90:91], 0
	v_mov_b64_e32 v[92:93], 0
	v_mov_b64_e32 v[94:95], 0
	v_mov_b64_e32 v[96:97], 0
	v_mov_b64_e32 v[98:99], 0
	v_mov_b64_e32 v[100:101], 0
	v_mov_b64_e32 v[102:103], 0
	v_mov_b64_e32 v[104:105], 0
	v_mov_b64_e32 v[106:107], 0
	v_mov_b64_e32 v[108:109], 0
	v_mov_b64_e32 v[110:111], 0
	v_mov_b64_e32 v[112:113], 0
	v_mov_b64_e32 v[114:115], 0
	v_mov_b64_e32 v[116:117], 0
	v_mov_b64_e32 v[118:119], 0
	v_mov_b64_e32 v[120:121], 0
	v_mov_b64_e32 v[122:123], 0
	v_mov_b64_e32 v[124:125], 0
	v_mov_b64_e32 v[126:127], 0
	v_add_u32_e32 v166, 0x10000, v215
	ds_read_b128 v[128:131], v166
	ds_read_b128 v[158:161], v166 offset:1024
	ds_read_b128 v[162:165], v166 offset:2048
	ds_read_b128 v[166:169], v166 offset:3072
	v_readfirstlane_b32 s98, v135
	s_cmpk_gt_u32 s98, 0xff
	s_cbranch_scc0 .Lkprio_1
	s_setprio 1
.Lkprio_1:
.LBB0_145:
	s_add_u32 s6, s2, 0xfffc0080
	s_addc_u32 s7, s3, -1
	s_add_i32 s29, 0, 0x10000
	s_cmp_eq_u32 s28, 12
	s_cselect_b32 s11, s9, s7
	s_cselect_b32 s10, s12, s6
	s_cselect_b32 s7, s13, s27
	s_cselect_b32 s6, s17, s19
	s_add_i32 m0, s50, 0xc000
	ds_read_b128 v[170:173], v216
	ds_read_b128 v[178:181], v216 offset:2048
	ds_read_b128 v[186:189], v216 offset:4096
	ds_read_b128 v[222:225], v216 offset:6144
	ds_read_b128 v[174:177], v216 offset:1024
	ds_read_b128 v[182:185], v216 offset:3072
	ds_read_b128 v[218:221], v216 offset:5120
	ds_read_b128 v[226:229], v216 offset:7168
	global_load_lds_dwordx4 v154, s[2:3]
	s_add_i32 m0, s50, 0xe000
	s_nop 0
	global_load_lds_dwordx4 v156, s[2:3]
	s_waitcnt lgkmcnt(8)
	s_waitcnt vmcnt(10)
	s_barrier
	s_waitcnt lgkmcnt(4)
	v_mfma_f32_16x16x32_bf16 v[124:127], v[128:131], v[170:173], v[124:127]
	v_mfma_f32_16x16x32_bf16 v[120:123], v[162:165], v[170:173], v[120:123]
	v_mfma_f32_16x16x32_bf16 v[108:111], v[128:131], v[178:181], v[108:111]
	v_mfma_f32_16x16x32_bf16 v[104:107], v[162:165], v[178:181], v[104:107]
	v_mfma_f32_16x16x32_bf16 v[92:95], v[128:131], v[186:189], v[92:95]
	v_mfma_f32_16x16x32_bf16 v[88:91], v[162:165], v[186:189], v[88:91]
	v_mfma_f32_16x16x32_bf16 v[76:79], v[128:131], v[222:225], v[76:79]
	v_mfma_f32_16x16x32_bf16 v[72:75], v[162:165], v[222:225], v[72:75]
	s_waitcnt lgkmcnt(0)
	v_mfma_f32_16x16x32_bf16 v[124:127], v[158:161], v[174:177], v[124:127]
	v_mfma_f32_16x16x32_bf16 v[120:123], v[166:169], v[174:177], v[120:123]
	v_mfma_f32_16x16x32_bf16 v[108:111], v[158:161], v[182:185], v[108:111]
	v_mfma_f32_16x16x32_bf16 v[104:107], v[166:169], v[182:185], v[104:107]
	v_mfma_f32_16x16x32_bf16 v[92:95], v[158:161], v[218:221], v[92:95]
	v_mfma_f32_16x16x32_bf16 v[88:91], v[166:169], v[218:221], v[88:91]
	v_mfma_f32_16x16x32_bf16 v[76:79], v[158:161], v[226:229], v[76:79]
	v_mfma_f32_16x16x32_bf16 v[72:75], v[166:169], v[226:229], v[72:75]
	s_barrier
	s_add_i32 s34, 0, 0x14000
	s_add_i32 s29, s29, s15
	v_add_u32_e32 v132, s34, v215
	s_mov_b32 m0, s29
	ds_read_b128 v[230:233], v132
	ds_read_b128 v[238:241], v132 offset:2048
	ds_read_b128 v[234:237], v132 offset:1024
	ds_read_b128 v[242:245], v132 offset:3072
	global_load_lds_dwordx4 v150, s[6:7]
	s_add_i32 m0, s29, 0x2000
	s_nop 0
	global_load_lds_dwordx4 v152, s[6:7]
	s_waitcnt vmcnt(10)
	s_barrier
	s_waitcnt lgkmcnt(2)
	v_mfma_f32_16x16x32_bf16 v[116:119], v[230:233], v[170:173], v[116:119]
	v_mfma_f32_16x16x32_bf16 v[112:115], v[238:241], v[170:173], v[112:115]
	v_mfma_f32_16x16x32_bf16 v[100:103], v[230:233], v[178:181], v[100:103]
	v_mfma_f32_16x16x32_bf16 v[96:99], v[238:241], v[178:181], v[96:99]
	v_mfma_f32_16x16x32_bf16 v[84:87], v[230:233], v[186:189], v[84:87]
	v_mfma_f32_16x16x32_bf16 v[80:83], v[238:241], v[186:189], v[80:83]
	v_mfma_f32_16x16x32_bf16 v[68:71], v[230:233], v[222:225], v[68:71]
	v_mfma_f32_16x16x32_bf16 v[64:67], v[238:241], v[222:225], v[64:67]
	s_waitcnt lgkmcnt(0)
	v_mfma_f32_16x16x32_bf16 v[116:119], v[234:237], v[174:177], v[116:119]
	v_mfma_f32_16x16x32_bf16 v[112:115], v[242:245], v[174:177], v[112:115]
	v_mfma_f32_16x16x32_bf16 v[100:103], v[234:237], v[182:185], v[100:103]
	v_mfma_f32_16x16x32_bf16 v[96:99], v[242:245], v[182:185], v[96:99]
	v_mfma_f32_16x16x32_bf16 v[84:87], v[234:237], v[218:221], v[84:87]
	v_mfma_f32_16x16x32_bf16 v[80:83], v[242:245], v[218:221], v[80:83]
	v_mfma_f32_16x16x32_bf16 v[68:71], v[234:237], v[226:229], v[68:71]
	v_mfma_f32_16x16x32_bf16 v[64:67], v[242:245], v[226:229], v[64:67]
	s_mov_b32 m0, s50
	v_lshl_add_u64 v[248:249], s[10:11], 0, v[150:151]
	s_barrier
	ds_read_b128 v[170:173], v216 offset:16384
	ds_read_b128 v[178:181], v216 offset:18432
	ds_read_b128 v[186:189], v216 offset:20480
	ds_read_b128 v[222:225], v216 offset:22528
	ds_read_b128 v[174:177], v216 offset:17408
	ds_read_b128 v[182:185], v216 offset:19456
	ds_read_b128 v[218:221], v216 offset:21504
	ds_read_b128 v[226:229], v216 offset:23552
	global_load_lds_dwordx4 v150, s[10:11]
	v_lshl_add_u64 v[250:251], s[10:11], 0, v[152:153]
	s_mov_b32 m0, s51
	s_nop 0
	global_load_lds_dwordx4 v152, s[10:11]
	s_waitcnt vmcnt(10)
	s_barrier
	s_waitcnt lgkmcnt(4)
	v_mfma_f32_16x16x32_bf16 v[60:63], v[128:131], v[170:173], v[60:63]
	v_mfma_f32_16x16x32_bf16 v[56:59], v[162:165], v[170:173], v[56:59]
	v_mfma_f32_16x16x32_bf16 v[44:47], v[128:131], v[178:181], v[44:47]
	v_mfma_f32_16x16x32_bf16 v[40:43], v[162:165], v[178:181], v[40:43]
	v_mfma_f32_16x16x32_bf16 v[28:31], v[128:131], v[186:189], v[28:31]
	v_mfma_f32_16x16x32_bf16 v[24:27], v[162:165], v[186:189], v[24:27]
	v_mfma_f32_16x16x32_bf16 v[12:15], v[128:131], v[222:225], v[12:15]
	v_mfma_f32_16x16x32_bf16 v[8:11], v[162:165], v[222:225], v[8:11]
	s_waitcnt lgkmcnt(0)
	v_mfma_f32_16x16x32_bf16 v[60:63], v[158:161], v[174:177], v[60:63]
	v_mfma_f32_16x16x32_bf16 v[56:59], v[166:169], v[174:177], v[56:59]
	v_mfma_f32_16x16x32_bf16 v[44:47], v[158:161], v[182:185], v[44:47]
	v_mfma_f32_16x16x32_bf16 v[40:43], v[166:169], v[182:185], v[40:43]
	v_mfma_f32_16x16x32_bf16 v[28:31], v[158:161], v[218:221], v[28:31]
	v_mfma_f32_16x16x32_bf16 v[24:27], v[166:169], v[218:221], v[24:27]
	v_mfma_f32_16x16x32_bf16 v[12:15], v[158:161], v[226:229], v[12:15]
	v_mfma_f32_16x16x32_bf16 v[8:11], v[166:169], v[226:229], v[8:11]
	s_barrier
	s_add_u32 s30, s6, 0x40000
	s_addc_u32 s31, s7, 0
	s_add_i32 s29, s34, s15
	s_mov_b32 m0, s29
	s_nop 0
	global_load_lds_dwordx4 v150, s[30:31]
	s_add_i32 m0, s29, 0x2000
	s_nop 0
	global_load_lds_dwordx4 v152, s[30:31]
	v_add_u32_e32 v166, 0x18000, v215
	ds_read_b128 v[128:131], v166
	ds_read_b128 v[158:161], v166 offset:1024
	ds_read_b128 v[162:165], v166 offset:2048
	ds_read_b128 v[166:169], v166 offset:3072
	s_waitcnt vmcnt(10)
	s_barrier
	v_mfma_f32_16x16x32_bf16 v[52:55], v[230:233], v[170:173], v[52:55]
	v_mfma_f32_16x16x32_bf16 v[48:51], v[238:241], v[170:173], v[48:51]
	v_mfma_f32_16x16x32_bf16 v[36:39], v[230:233], v[178:181], v[36:39]
	v_mfma_f32_16x16x32_bf16 v[32:35], v[238:241], v[178:181], v[32:35]
	v_mfma_f32_16x16x32_bf16 v[20:23], v[230:233], v[186:189], v[20:23]
	v_mfma_f32_16x16x32_bf16 v[16:19], v[238:241], v[186:189], v[16:19]
	v_mfma_f32_16x16x32_bf16 v[4:7], v[230:233], v[222:225], v[4:7]
	v_mfma_f32_16x16x32_bf16 v[0:3], v[238:241], v[222:225], v[0:3]
	v_mfma_f32_16x16x32_bf16 v[52:55], v[234:237], v[174:177], v[52:55]
	v_mfma_f32_16x16x32_bf16 v[48:51], v[242:245], v[174:177], v[48:51]
	v_mfma_f32_16x16x32_bf16 v[36:39], v[234:237], v[182:185], v[36:39]
	v_mfma_f32_16x16x32_bf16 v[32:35], v[242:245], v[182:185], v[32:35]
	v_mfma_f32_16x16x32_bf16 v[20:23], v[234:237], v[218:221], v[20:23]
	v_mfma_f32_16x16x32_bf16 v[16:19], v[242:245], v[218:221], v[16:19]
	v_mfma_f32_16x16x32_bf16 v[4:7], v[234:237], v[226:229], v[4:7]
	v_mfma_f32_16x16x32_bf16 v[0:3], v[242:245], v[226:229], v[0:3]
	s_add_i32 s29, 0, 0x18000
	s_barrier
	s_add_u32 s10, s10, 0x40000
	s_addc_u32 s11, s11, 0
	s_mov_b32 m0, s36
	ds_read_b128 v[170:173], v216 offset:32768
	ds_read_b128 v[178:181], v216 offset:34816
	ds_read_b128 v[186:189], v216 offset:36864
	ds_read_b128 v[222:225], v216 offset:38912
	ds_read_b128 v[174:177], v216 offset:33792
	ds_read_b128 v[182:185], v216 offset:35840
	ds_read_b128 v[218:221], v216 offset:37888
	ds_read_b128 v[226:229], v216 offset:39936
	global_load_lds_dwordx4 v150, s[10:11]
	s_mov_b32 m0, s37
	s_nop 0
	global_load_lds_dwordx4 v152, s[10:11]
	s_waitcnt lgkmcnt(8)
	s_waitcnt vmcnt(10)
	s_barrier
	s_waitcnt lgkmcnt(4)
	v_mfma_f32_16x16x32_bf16 v[124:127], v[128:131], v[170:173], v[124:127]
	v_mfma_f32_16x16x32_bf16 v[120:123], v[162:165], v[170:173], v[120:123]
	v_mfma_f32_16x16x32_bf16 v[108:111], v[128:131], v[178:181], v[108:111]
	v_mfma_f32_16x16x32_bf16 v[104:107], v[162:165], v[178:181], v[104:107]
	v_mfma_f32_16x16x32_bf16 v[92:95], v[128:131], v[186:189], v[92:95]
	v_mfma_f32_16x16x32_bf16 v[88:91], v[162:165], v[186:189], v[88:91]
	v_mfma_f32_16x16x32_bf16 v[76:79], v[128:131], v[222:225], v[76:79]
	v_mfma_f32_16x16x32_bf16 v[72:75], v[162:165], v[222:225], v[72:75]
	s_waitcnt lgkmcnt(0)
	v_mfma_f32_16x16x32_bf16 v[124:127], v[158:161], v[174:177], v[124:127]
	v_mfma_f32_16x16x32_bf16 v[120:123], v[166:169], v[174:177], v[120:123]
	v_mfma_f32_16x16x32_bf16 v[108:111], v[158:161], v[182:185], v[108:111]
	v_mfma_f32_16x16x32_bf16 v[104:107], v[166:169], v[182:185], v[104:107]
	v_mfma_f32_16x16x32_bf16 v[92:95], v[158:161], v[218:221], v[92:95]
	v_mfma_f32_16x16x32_bf16 v[88:91], v[166:169], v[218:221], v[88:91]
	v_mfma_f32_16x16x32_bf16 v[76:79], v[158:161], v[226:229], v[76:79]
	v_mfma_f32_16x16x32_bf16 v[72:75], v[166:169], v[226:229], v[72:75]
	s_barrier
	s_add_i32 s10, 0, 0x1c000
	s_add_i32 s11, s29, s15
	v_add_u32_e32 v132, s10, v215
	s_mov_b32 m0, s11
	ds_read_b128 v[230:233], v132
	ds_read_b128 v[238:241], v132 offset:2048
	ds_read_b128 v[234:237], v132 offset:1024
	ds_read_b128 v[242:245], v132 offset:3072
	s_add_u32 s98, s6, 0x80
	s_addc_u32 s99, s7, 0
	global_load_lds_dwordx4 v150, s[98:99]
	s_add_i32 m0, s11, 0x2000
	s_nop 0
	global_load_lds_dwordx4 v152, s[98:99]
	s_waitcnt vmcnt(10)
	s_barrier
	s_waitcnt lgkmcnt(2)
	v_mfma_f32_16x16x32_bf16 v[116:119], v[230:233], v[170:173], v[116:119]
	v_mfma_f32_16x16x32_bf16 v[112:115], v[238:241], v[170:173], v[112:115]
	v_mfma_f32_16x16x32_bf16 v[100:103], v[230:233], v[178:181], v[100:103]
	v_mfma_f32_16x16x32_bf16 v[96:99], v[238:241], v[178:181], v[96:99]
	v_mfma_f32_16x16x32_bf16 v[84:87], v[230:233], v[186:189], v[84:87]
	v_mfma_f32_16x16x32_bf16 v[80:83], v[238:241], v[186:189], v[80:83]
	v_mfma_f32_16x16x32_bf16 v[68:71], v[230:233], v[222:225], v[68:71]
	v_mfma_f32_16x16x32_bf16 v[64:67], v[238:241], v[222:225], v[64:67]
	s_waitcnt lgkmcnt(0)
	v_mfma_f32_16x16x32_bf16 v[116:119], v[234:237], v[174:177], v[116:119]
	v_mfma_f32_16x16x32_bf16 v[112:115], v[242:245], v[174:177], v[112:115]
	v_mfma_f32_16x16x32_bf16 v[100:103], v[234:237], v[182:185], v[100:103]
	v_mfma_f32_16x16x32_bf16 v[96:99], v[242:245], v[182:185], v[96:99]
	v_mfma_f32_16x16x32_bf16 v[84:87], v[234:237], v[218:221], v[84:87]
	v_mfma_f32_16x16x32_bf16 v[80:83], v[242:245], v[218:221], v[80:83]
	v_mfma_f32_16x16x32_bf16 v[68:71], v[234:237], v[226:229], v[68:71]
	v_mfma_f32_16x16x32_bf16 v[64:67], v[242:245], v[226:229], v[64:67]
	s_mov_b32 m0, s52
	v_lshl_add_u64 v[190:191], v[248:249], 0, s[66:67]
	s_barrier
	ds_read_b128 v[170:173], v216 offset:49152
	ds_read_b128 v[178:181], v216 offset:51200
	ds_read_b128 v[186:189], v216 offset:53248
	ds_read_b128 v[222:225], v216 offset:55296
	ds_read_b128 v[174:177], v216 offset:50176
	ds_read_b128 v[182:185], v216 offset:52224
	ds_read_b128 v[218:221], v216 offset:54272
	ds_read_b128 v[226:229], v216 offset:56320
	global_load_lds_dwordx4 v[190:191], off
	v_lshl_add_u64 v[190:191], v[250:251], 0, s[66:67]
	s_mov_b32 m0, s53
	s_nop 0
	global_load_lds_dwordx4 v[190:191], off
	s_waitcnt vmcnt(10)
	s_barrier
	s_waitcnt lgkmcnt(4)
	v_mfma_f32_16x16x32_bf16 v[60:63], v[128:131], v[170:173], v[60:63]
	v_mfma_f32_16x16x32_bf16 v[56:59], v[162:165], v[170:173], v[56:59]
	v_mfma_f32_16x16x32_bf16 v[44:47], v[128:131], v[178:181], v[44:47]
	v_mfma_f32_16x16x32_bf16 v[40:43], v[162:165], v[178:181], v[40:43]
	v_mfma_f32_16x16x32_bf16 v[28:31], v[128:131], v[186:189], v[28:31]
	v_mfma_f32_16x16x32_bf16 v[24:27], v[162:165], v[186:189], v[24:27]
	v_mfma_f32_16x16x32_bf16 v[12:15], v[128:131], v[222:225], v[12:15]
	v_mfma_f32_16x16x32_bf16 v[8:11], v[162:165], v[222:225], v[8:11]
	s_waitcnt lgkmcnt(0)
	v_mfma_f32_16x16x32_bf16 v[60:63], v[158:161], v[174:177], v[60:63]
	v_mfma_f32_16x16x32_bf16 v[56:59], v[166:169], v[174:177], v[56:59]
	v_mfma_f32_16x16x32_bf16 v[44:47], v[158:161], v[182:185], v[44:47]
	v_mfma_f32_16x16x32_bf16 v[40:43], v[166:169], v[182:185], v[40:43]
	v_mfma_f32_16x16x32_bf16 v[28:31], v[158:161], v[218:221], v[28:31]
	v_mfma_f32_16x16x32_bf16 v[24:27], v[166:169], v[218:221], v[24:27]
	v_mfma_f32_16x16x32_bf16 v[12:15], v[158:161], v[226:229], v[12:15]
	v_mfma_f32_16x16x32_bf16 v[8:11], v[166:169], v[226:229], v[8:11]
	s_barrier
	s_add_u32 s6, s6, 0x40080
	s_addc_u32 s7, s7, 0
	s_add_i32 s10, s10, s15
	s_mov_b32 m0, s10
	s_nop 0
	global_load_lds_dwordx4 v150, s[6:7]
	s_add_i32 m0, s10, 0x2000
	s_nop 0
	global_load_lds_dwordx4 v152, s[6:7]
	v_add_u32_e32 v166, 0x10000, v215
	ds_read_b128 v[128:131], v166
	ds_read_b128 v[158:161], v166 offset:1024
	ds_read_b128 v[162:165], v166 offset:2048
	ds_read_b128 v[166:169], v166 offset:3072
	s_waitcnt vmcnt(10)
	s_barrier
	v_mfma_f32_16x16x32_bf16 v[52:55], v[230:233], v[170:173], v[52:55]
	v_mfma_f32_16x16x32_bf16 v[48:51], v[238:241], v[170:173], v[48:51]
	v_mfma_f32_16x16x32_bf16 v[36:39], v[230:233], v[178:181], v[36:39]
	v_mfma_f32_16x16x32_bf16 v[32:35], v[238:241], v[178:181], v[32:35]
	v_mfma_f32_16x16x32_bf16 v[20:23], v[230:233], v[186:189], v[20:23]
	v_mfma_f32_16x16x32_bf16 v[16:19], v[238:241], v[186:189], v[16:19]
	v_mfma_f32_16x16x32_bf16 v[4:7], v[230:233], v[222:225], v[4:7]
	v_mfma_f32_16x16x32_bf16 v[0:3], v[238:241], v[222:225], v[0:3]
	v_mfma_f32_16x16x32_bf16 v[52:55], v[234:237], v[174:177], v[52:55]
	v_mfma_f32_16x16x32_bf16 v[48:51], v[242:245], v[174:177], v[48:51]
	v_mfma_f32_16x16x32_bf16 v[36:39], v[234:237], v[182:185], v[36:39]
	v_mfma_f32_16x16x32_bf16 v[32:35], v[242:245], v[182:185], v[32:35]
	v_mfma_f32_16x16x32_bf16 v[20:23], v[234:237], v[218:221], v[20:23]
	v_mfma_f32_16x16x32_bf16 v[16:19], v[242:245], v[218:221], v[16:19]
	v_mfma_f32_16x16x32_bf16 v[4:7], v[234:237], v[226:229], v[4:7]
	v_mfma_f32_16x16x32_bf16 v[0:3], v[242:245], v[226:229], v[0:3]
	s_add_i32 s28, s28, 2
	s_add_u32 s2, s2, 0x100
	s_addc_u32 s3, s3, 0
	s_add_u32 s19, s19, 0x100
	s_addc_u32 s27, s27, 0
	s_cmp_gt_u32 s28, 13
	s_barrier
	s_cbranch_scc0 .LBB0_145
	s_setprio 0
	s_waitcnt lgkmcnt(0)
	v_mov_b32_e32 v166, v135
	s_mov_b64 s[2:3], s[0:1]
	v_readfirstlane_b32 s27, v166
	s_bfe_u32 s19, s27, 0x20006
	s_load_dwordx2 s[30:31], s[2:3], 0x88
	s_mov_b64 s[2:3], s[0:1]
	s_cmp_gt_i32 s8, 31
	s_load_dwordx2 s[28:29], s[2:3], 0x80
	s_cselect_b64 s[6:7], -1, 0
	s_cmp_lt_i32 s8, 32
	s_cselect_b64 s[2:3], -1, 0
	s_ashr_i32 s9, s27, 2
	s_lshl_b32 s8, s8, 8
	s_and_b32 s17, s9, 0xffffffc0
	v_and_b32_e32 v217, 15, v166
	s_add_i32 s17, s17, s8
	v_bfe_u32 v186, v166, 4, 2
	v_or_b32_e32 v158, s17, v217
	s_cmp_gt_i32 s26, 3
	s_mov_b64 s[8:9], -1
	s_cbranch_scc0 .LBB0_829
	s_cmp_gt_u32 s26, 5
	s_cbranch_scc0 .LBB0_409
	s_cmp_gt_u32 s26, 8
	s_cbranch_scc0 .LBB0_406
	s_waitcnt lgkmcnt(0)
	v_and_b32_e32 v128, 1, v166
	v_cmp_eq_u32_e64 s[8:9], 0, v128
	v_cmp_eq_u32_e32 vcc, 1, v128
	s_mov_b32 s10, 0x05040100
	s_mov_b32 s11, 0x07060302
	s_cmp_eq_u32 s6, 0
	s_cbranch_scc1 .Lvf_f_c

.LBB0_1103:
	s_ashr_i32 s9, s8, 31
	v_cmp_lt_i64_e32 vcc, s[10:11], v[144:145]
	s_lshl_b64 s[10:11], s[8:9], 19
	s_add_u32 s10, s15, s10
	s_addc_u32 s11, s26, s11
	s_and_b64 s[12:13], vcc, exec
	s_cselect_b32 s9, s11, s19
	s_cselect_b32 s42, s10, s18
	s_ashr_i32 s7, s6, 31
	s_lshl_b64 s[12:13], s[6:7], 19
	s_add_u32 s12, s27, s12
	s_addc_u32 s13, s28, s13
	s_and_b64 s[24:25], vcc, exec
	s_cselect_b32 s7, s13, s23
	s_cselect_b32 s43, s12, s22
	s_add_u32 s18, s18, 0x40080
	s_addc_u32 s19, s19, 0
	s_add_u32 s44, s22, 0x100
	v_mov_b32_e32 v0, 0
	s_addc_u32 s45, s23, 0
	s_mov_b32 s46, -2
	v_mov_b32_e32 v1, v0
	v_mov_b64_e32 v[2:3], 0
	v_mov_b64_e32 v[4:5], 0
	v_mov_b64_e32 v[6:7], 0
	v_mov_b64_e32 v[8:9], 0
	v_mov_b64_e32 v[10:11], 0
	v_mov_b64_e32 v[12:13], 0
	v_mov_b64_e32 v[14:15], 0
	v_mov_b64_e32 v[16:17], 0
	v_mov_b64_e32 v[18:19], 0
	v_mov_b64_e32 v[20:21], 0
	v_mov_b64_e32 v[22:23], 0
	v_mov_b64_e32 v[24:25], 0
	v_mov_b64_e32 v[26:27], 0
	v_mov_b64_e32 v[28:29], 0
	v_mov_b64_e32 v[30:31], 0
	v_mov_b64_e32 v[32:33], 0
	v_mov_b64_e32 v[34:35], 0
	v_mov_b64_e32 v[36:37], 0
	v_mov_b64_e32 v[38:39], 0
	v_mov_b64_e32 v[40:41], 0
	v_mov_b64_e32 v[42:43], 0
	v_mov_b64_e32 v[44:45], 0
	v_mov_b64_e32 v[46:47], 0
	v_mov_b64_e32 v[48:49], 0
	v_mov_b64_e32 v[50:51], 0
	v_mov_b64_e32 v[52:53], 0
	v_mov_b64_e32 v[54:55], 0
	v_mov_b64_e32 v[56:57], 0
	v_mov_b64_e32 v[58:59], 0
	v_mov_b64_e32 v[60:61], 0
	v_mov_b64_e32 v[62:63], 0
	v_mov_b64_e32 v[64:65], 0
	v_mov_b64_e32 v[66:67], 0
	v_mov_b64_e32 v[68:69], 0
	v_mov_b64_e32 v[70:71], 0
	v_mov_b64_e32 v[72:73], 0
	v_mov_b64_e32 v[74:75], 0
	v_mov_b64_e32 v[76:77], 0
	v_mov_b64_e32 v[78:79], 0
	v_mov_b64_e32 v[80:81], 0
	v_mov_b64_e32 v[82:83], 0
	v_mov_b64_e32 v[84:85], 0
	v_mov_b64_e32 v[86:87], 0
	v_mov_b64_e32 v[88:89], 0
	v_mov_b64_e32 v[90:91], 0
	v_mov_b64_e32 v[92:93], 0
	v_mov_b64_e32 v[94:95], 0
	v_mov_b64_e32 v[96:97], 0
	v_mov_b64_e32 v[98:99], 0
	v_mov_b64_e32 v[100:101], 0
	v_mov_b64_e32 v[102:103], 0
	v_mov_b64_e32 v[104:105], 0
	v_mov_b64_e32 v[106:107], 0
	v_mov_b64_e32 v[108:109], 0
	v_mov_b64_e32 v[110:111], 0
	v_mov_b64_e32 v[112:113], 0
	v_mov_b64_e32 v[114:115], 0
	v_mov_b64_e32 v[116:117], 0
	v_mov_b64_e32 v[118:119], 0
	v_mov_b64_e32 v[120:121], 0
	v_mov_b64_e32 v[122:123], 0
	v_mov_b64_e32 v[124:125], 0
	v_mov_b64_e32 v[126:127], 0
	v_add_u32_e32 v168, 0x10000, v154
	ds_read_b128 v[156:159], v168
	ds_read_b128 v[160:163], v168 offset:1024
	ds_read_b128 v[164:167], v168 offset:2048
	ds_read_b128 v[168:171], v168 offset:3072
	v_readfirstlane_b32 s98, v135
	s_cmpk_gt_u32 s98, 0xff
	s_cbranch_scc0 .Lkprio_2
	s_setprio 1
.Lkprio_2:
.LBB0_1104:
	s_add_u32 s22, s18, 0xfffc0080
	s_addc_u32 s23, s19, -1
	s_add_i32 s47, 0, 0x10000
	s_cmp_eq_u32 s46, 12
	s_cselect_b32 s25, s9, s23
	s_cselect_b32 s24, s42, s22
	s_cselect_b32 s23, s7, s45
	s_cselect_b32 s22, s43, s44
	s_add_i32 m0, s17, 0xc000
	ds_read_b128 v[172:175], v155
	ds_read_b128 v[180:183], v155 offset:2048
	ds_read_b128 v[188:191], v155 offset:4096
	ds_read_b128 v[220:223], v155 offset:6144
	ds_read_b128 v[176:179], v155 offset:1024
	ds_read_b128 v[184:187], v155 offset:3072
	ds_read_b128 v[216:219], v155 offset:5120
	ds_read_b128 v[224:227], v155 offset:7168
	global_load_lds_dwordx4 v130, s[18:19]
	s_add_i32 m0, s17, 0xe000
	s_nop 0
	global_load_lds_dwordx4 v150, s[18:19]
	s_waitcnt lgkmcnt(8)
	s_waitcnt vmcnt(10)
	s_barrier
	s_waitcnt lgkmcnt(4)
	v_mfma_f32_16x16x32_bf16 v[124:127], v[156:159], v[172:175], v[124:127]
	v_mfma_f32_16x16x32_bf16 v[120:123], v[164:167], v[172:175], v[120:123]
	v_mfma_f32_16x16x32_bf16 v[108:111], v[156:159], v[180:183], v[108:111]
	v_mfma_f32_16x16x32_bf16 v[104:107], v[164:167], v[180:183], v[104:107]
	v_mfma_f32_16x16x32_bf16 v[92:95], v[156:159], v[188:191], v[92:95]
	v_mfma_f32_16x16x32_bf16 v[88:91], v[164:167], v[188:191], v[88:91]
	v_mfma_f32_16x16x32_bf16 v[76:79], v[156:159], v[220:223], v[76:79]
	v_mfma_f32_16x16x32_bf16 v[72:75], v[164:167], v[220:223], v[72:75]
	s_waitcnt lgkmcnt(0)
	v_mfma_f32_16x16x32_bf16 v[124:127], v[160:163], v[176:179], v[124:127]
	v_mfma_f32_16x16x32_bf16 v[120:123], v[168:171], v[176:179], v[120:123]
	v_mfma_f32_16x16x32_bf16 v[108:111], v[160:163], v[184:187], v[108:111]
	v_mfma_f32_16x16x32_bf16 v[104:107], v[168:171], v[184:187], v[104:107]
	v_mfma_f32_16x16x32_bf16 v[92:95], v[160:163], v[216:219], v[92:95]
	v_mfma_f32_16x16x32_bf16 v[88:91], v[168:171], v[216:219], v[88:91]
	v_mfma_f32_16x16x32_bf16 v[76:79], v[160:163], v[224:227], v[76:79]
	v_mfma_f32_16x16x32_bf16 v[72:75], v[168:171], v[224:227], v[72:75]
	s_barrier
	s_add_i32 s50, 0, 0x14000
	v_add_u32_e32 v152, s50, v154
	s_add_i32 s47, s47, s29
	ds_read_b128 v[228:231], v152
	ds_read_b128 v[236:239], v152 offset:2048
	ds_read_b128 v[232:235], v152 offset:1024
	ds_read_b128 v[240:243], v152 offset:3072
	s_mov_b32 m0, s47
	s_nop 0
	global_load_lds_dwordx4 v132, s[22:23]
	s_add_i32 m0, s47, 0x2000
	s_nop 0
	global_load_lds_dwordx4 v128, s[22:23]
	s_waitcnt vmcnt(10)
	s_barrier
	s_waitcnt lgkmcnt(2)
	v_mfma_f32_16x16x32_bf16 v[116:119], v[228:231], v[172:175], v[116:119]
	v_mfma_f32_16x16x32_bf16 v[112:115], v[236:239], v[172:175], v[112:115]
	v_mfma_f32_16x16x32_bf16 v[100:103], v[228:231], v[180:183], v[100:103]
	v_mfma_f32_16x16x32_bf16 v[96:99], v[236:239], v[180:183], v[96:99]
	v_mfma_f32_16x16x32_bf16 v[84:87], v[228:231], v[188:191], v[84:87]
	v_mfma_f32_16x16x32_bf16 v[80:83], v[236:239], v[188:191], v[80:83]
	v_mfma_f32_16x16x32_bf16 v[68:71], v[228:231], v[220:223], v[68:71]
	v_mfma_f32_16x16x32_bf16 v[64:67], v[236:239], v[220:223], v[64:67]
	s_waitcnt lgkmcnt(0)
	v_mfma_f32_16x16x32_bf16 v[116:119], v[232:235], v[176:179], v[116:119]
	v_mfma_f32_16x16x32_bf16 v[112:115], v[240:243], v[176:179], v[112:115]
	v_mfma_f32_16x16x32_bf16 v[100:103], v[232:235], v[184:187], v[100:103]
	v_mfma_f32_16x16x32_bf16 v[96:99], v[240:243], v[184:187], v[96:99]
	v_mfma_f32_16x16x32_bf16 v[84:87], v[232:235], v[216:219], v[84:87]
	v_mfma_f32_16x16x32_bf16 v[80:83], v[240:243], v[216:219], v[80:83]
	v_mfma_f32_16x16x32_bf16 v[68:71], v[232:235], v[224:227], v[68:71]
	v_mfma_f32_16x16x32_bf16 v[64:67], v[240:243], v[224:227], v[64:67]
	s_mov_b32 m0, s17
	v_lshl_add_u64 v[246:247], s[24:25], 0, v[132:133]
	s_barrier
	ds_read_b128 v[172:175], v155 offset:16384
	ds_read_b128 v[180:183], v155 offset:18432
	ds_read_b128 v[188:191], v155 offset:20480
	ds_read_b128 v[220:223], v155 offset:22528
	ds_read_b128 v[176:179], v155 offset:17408
	ds_read_b128 v[184:187], v155 offset:19456
	ds_read_b128 v[216:219], v155 offset:21504
	ds_read_b128 v[224:227], v155 offset:23552
	global_load_lds_dwordx4 v132, s[24:25]
	v_lshl_add_u64 v[248:249], s[24:25], 0, v[128:129]
	s_mov_b32 m0, s31
	s_nop 0
	global_load_lds_dwordx4 v128, s[24:25]
	s_waitcnt vmcnt(10)
	s_barrier
	s_waitcnt lgkmcnt(4)
	v_mfma_f32_16x16x32_bf16 v[60:63], v[156:159], v[172:175], v[60:63]
	v_mfma_f32_16x16x32_bf16 v[56:59], v[164:167], v[172:175], v[56:59]
	v_mfma_f32_16x16x32_bf16 v[44:47], v[156:159], v[180:183], v[44:47]
	v_mfma_f32_16x16x32_bf16 v[40:43], v[164:167], v[180:183], v[40:43]
	v_mfma_f32_16x16x32_bf16 v[28:31], v[156:159], v[188:191], v[28:31]
	v_mfma_f32_16x16x32_bf16 v[24:27], v[164:167], v[188:191], v[24:27]
	v_mfma_f32_16x16x32_bf16 v[12:15], v[156:159], v[220:223], v[12:15]
	v_mfma_f32_16x16x32_bf16 v[8:11], v[164:167], v[220:223], v[8:11]
	s_waitcnt lgkmcnt(0)
	v_mfma_f32_16x16x32_bf16 v[60:63], v[160:163], v[176:179], v[60:63]
	v_mfma_f32_16x16x32_bf16 v[56:59], v[168:171], v[176:179], v[56:59]
	v_mfma_f32_16x16x32_bf16 v[44:47], v[160:163], v[184:187], v[44:47]
	v_mfma_f32_16x16x32_bf16 v[40:43], v[168:171], v[184:187], v[40:43]
	v_mfma_f32_16x16x32_bf16 v[28:31], v[160:163], v[216:219], v[28:31]
	v_mfma_f32_16x16x32_bf16 v[24:27], v[168:171], v[216:219], v[24:27]
	v_mfma_f32_16x16x32_bf16 v[12:15], v[160:163], v[224:227], v[12:15]
	v_mfma_f32_16x16x32_bf16 v[8:11], v[168:171], v[224:227], v[8:11]
	s_barrier
	s_add_u32 s48, s22, 0x40000
	s_addc_u32 s49, s23, 0
	s_add_i32 s47, s50, s29
	s_mov_b32 m0, s47
	s_nop 0
	global_load_lds_dwordx4 v132, s[48:49]
	s_add_i32 m0, s47, 0x2000
	s_nop 0
	global_load_lds_dwordx4 v128, s[48:49]
	v_add_u32_e32 v168, 0x18000, v154
	ds_read_b128 v[156:159], v168
	ds_read_b128 v[160:163], v168 offset:1024
	ds_read_b128 v[164:167], v168 offset:2048
	ds_read_b128 v[168:171], v168 offset:3072
	s_waitcnt vmcnt(10)
	s_barrier
	v_mfma_f32_16x16x32_bf16 v[52:55], v[228:231], v[172:175], v[52:55]
	v_mfma_f32_16x16x32_bf16 v[48:51], v[236:239], v[172:175], v[48:51]
	v_mfma_f32_16x16x32_bf16 v[36:39], v[228:231], v[180:183], v[36:39]
	v_mfma_f32_16x16x32_bf16 v[32:35], v[236:239], v[180:183], v[32:35]
	v_mfma_f32_16x16x32_bf16 v[20:23], v[228:231], v[188:191], v[20:23]
	v_mfma_f32_16x16x32_bf16 v[16:19], v[236:239], v[188:191], v[16:19]
	v_mfma_f32_16x16x32_bf16 v[4:7], v[228:231], v[220:223], v[4:7]
	v_mfma_f32_16x16x32_bf16 v[0:3], v[236:239], v[220:223], v[0:3]
	v_mfma_f32_16x16x32_bf16 v[52:55], v[232:235], v[176:179], v[52:55]
	v_mfma_f32_16x16x32_bf16 v[48:51], v[240:243], v[176:179], v[48:51]
	v_mfma_f32_16x16x32_bf16 v[36:39], v[232:235], v[184:187], v[36:39]
	v_mfma_f32_16x16x32_bf16 v[32:35], v[240:243], v[184:187], v[32:35]
	v_mfma_f32_16x16x32_bf16 v[20:23], v[232:235], v[216:219], v[20:23]
	v_mfma_f32_16x16x32_bf16 v[16:19], v[240:243], v[216:219], v[16:19]
	v_mfma_f32_16x16x32_bf16 v[4:7], v[232:235], v[224:227], v[4:7]
	v_mfma_f32_16x16x32_bf16 v[0:3], v[240:243], v[224:227], v[0:3]
	s_add_i32 s47, 0, 0x18000
	s_barrier
	s_add_u32 s24, s24, 0x40000
	s_addc_u32 s25, s25, 0
	s_mov_b32 m0, s34
	ds_read_b128 v[172:175], v155 offset:32768
	ds_read_b128 v[180:183], v155 offset:34816
	ds_read_b128 v[188:191], v155 offset:36864
	ds_read_b128 v[220:223], v155 offset:38912
	ds_read_b128 v[176:179], v155 offset:33792
	ds_read_b128 v[184:187], v155 offset:35840
	ds_read_b128 v[216:219], v155 offset:37888
	ds_read_b128 v[224:227], v155 offset:39936
	global_load_lds_dwordx4 v132, s[24:25]
	s_mov_b32 m0, s35
	s_nop 0
	global_load_lds_dwordx4 v128, s[24:25]
	s_waitcnt lgkmcnt(8)
	s_waitcnt vmcnt(10)
	s_barrier
	s_waitcnt lgkmcnt(4)
	v_mfma_f32_16x16x32_bf16 v[124:127], v[156:159], v[172:175], v[124:127]
	v_mfma_f32_16x16x32_bf16 v[120:123], v[164:167], v[172:175], v[120:123]
	v_mfma_f32_16x16x32_bf16 v[108:111], v[156:159], v[180:183], v[108:111]
	v_mfma_f32_16x16x32_bf16 v[104:107], v[164:167], v[180:183], v[104:107]
	v_mfma_f32_16x16x32_bf16 v[92:95], v[156:159], v[188:191], v[92:95]
	v_mfma_f32_16x16x32_bf16 v[88:91], v[164:167], v[188:191], v[88:91]
	v_mfma_f32_16x16x32_bf16 v[76:79], v[156:159], v[220:223], v[76:79]
	v_mfma_f32_16x16x32_bf16 v[72:75], v[164:167], v[220:223], v[72:75]
	s_waitcnt lgkmcnt(0)
	v_mfma_f32_16x16x32_bf16 v[124:127], v[160:163], v[176:179], v[124:127]
	v_mfma_f32_16x16x32_bf16 v[120:123], v[168:171], v[176:179], v[120:123]
	v_mfma_f32_16x16x32_bf16 v[108:111], v[160:163], v[184:187], v[108:111]
	v_mfma_f32_16x16x32_bf16 v[104:107], v[168:171], v[184:187], v[104:107]
	v_mfma_f32_16x16x32_bf16 v[92:95], v[160:163], v[216:219], v[92:95]
	v_mfma_f32_16x16x32_bf16 v[88:91], v[168:171], v[216:219], v[88:91]
	v_mfma_f32_16x16x32_bf16 v[76:79], v[160:163], v[224:227], v[76:79]
	v_mfma_f32_16x16x32_bf16 v[72:75], v[168:171], v[224:227], v[72:75]
	s_barrier
	s_add_i32 s24, 0, 0x1c000
	s_add_i32 s25, s47, s29
	v_add_u32_e32 v200, s24, v154
	s_mov_b32 m0, s25
	ds_read_b128 v[228:231], v200
	ds_read_b128 v[236:239], v200 offset:2048
	ds_read_b128 v[232:235], v200 offset:1024
	ds_read_b128 v[240:243], v200 offset:3072
	s_add_u32 s98, s22, 0x80
	s_addc_u32 s99, s23, 0
	global_load_lds_dwordx4 v132, s[98:99]
	s_add_i32 m0, s25, 0x2000
	s_nop 0
	global_load_lds_dwordx4 v128, s[98:99]
	s_waitcnt vmcnt(10)
	s_barrier
	s_waitcnt lgkmcnt(2)
	v_mfma_f32_16x16x32_bf16 v[116:119], v[228:231], v[172:175], v[116:119]
	v_mfma_f32_16x16x32_bf16 v[112:115], v[236:239], v[172:175], v[112:115]
	v_mfma_f32_16x16x32_bf16 v[100:103], v[228:231], v[180:183], v[100:103]
	v_mfma_f32_16x16x32_bf16 v[96:99], v[236:239], v[180:183], v[96:99]
	v_mfma_f32_16x16x32_bf16 v[84:87], v[228:231], v[188:191], v[84:87]
	v_mfma_f32_16x16x32_bf16 v[80:83], v[236:239], v[188:191], v[80:83]
	v_mfma_f32_16x16x32_bf16 v[68:71], v[228:231], v[220:223], v[68:71]
	v_mfma_f32_16x16x32_bf16 v[64:67], v[236:239], v[220:223], v[64:67]
	s_waitcnt lgkmcnt(0)
	v_mfma_f32_16x16x32_bf16 v[116:119], v[232:235], v[176:179], v[116:119]
	v_mfma_f32_16x16x32_bf16 v[112:115], v[240:243], v[176:179], v[112:115]
	v_mfma_f32_16x16x32_bf16 v[100:103], v[232:235], v[184:187], v[100:103]
	v_mfma_f32_16x16x32_bf16 v[96:99], v[240:243], v[184:187], v[96:99]
	v_mfma_f32_16x16x32_bf16 v[84:87], v[232:235], v[216:219], v[84:87]
	v_mfma_f32_16x16x32_bf16 v[80:83], v[240:243], v[216:219], v[80:83]
	v_mfma_f32_16x16x32_bf16 v[68:71], v[232:235], v[224:227], v[68:71]
	v_mfma_f32_16x16x32_bf16 v[64:67], v[240:243], v[224:227], v[64:67]
	s_mov_b32 m0, s36
	v_lshl_add_u64 v[152:153], v[246:247], 0, s[66:67]
	s_barrier
	ds_read_b128 v[172:175], v155 offset:49152
	ds_read_b128 v[180:183], v155 offset:51200
	ds_read_b128 v[188:191], v155 offset:53248
	ds_read_b128 v[220:223], v155 offset:55296
	ds_read_b128 v[176:179], v155 offset:50176
	ds_read_b128 v[184:187], v155 offset:52224
	ds_read_b128 v[216:219], v155 offset:54272
	ds_read_b128 v[224:227], v155 offset:56320
	global_load_lds_dwordx4 v[152:153], off
	v_lshl_add_u64 v[152:153], v[248:249], 0, s[66:67]
	s_mov_b32 m0, s37
	s_nop 0
	global_load_lds_dwordx4 v[152:153], off
	s_waitcnt vmcnt(10)
	s_barrier
	s_waitcnt lgkmcnt(4)
	v_mfma_f32_16x16x32_bf16 v[60:63], v[156:159], v[172:175], v[60:63]
	v_mfma_f32_16x16x32_bf16 v[56:59], v[164:167], v[172:175], v[56:59]
	v_mfma_f32_16x16x32_bf16 v[44:47], v[156:159], v[180:183], v[44:47]
	v_mfma_f32_16x16x32_bf16 v[40:43], v[164:167], v[180:183], v[40:43]
	v_mfma_f32_16x16x32_bf16 v[28:31], v[156:159], v[188:191], v[28:31]
	v_mfma_f32_16x16x32_bf16 v[24:27], v[164:167], v[188:191], v[24:27]
	v_mfma_f32_16x16x32_bf16 v[12:15], v[156:159], v[220:223], v[12:15]
	v_mfma_f32_16x16x32_bf16 v[8:11], v[164:167], v[220:223], v[8:11]
	s_waitcnt lgkmcnt(0)
	v_mfma_f32_16x16x32_bf16 v[60:63], v[160:163], v[176:179], v[60:63]
	v_mfma_f32_16x16x32_bf16 v[56:59], v[168:171], v[176:179], v[56:59]
	v_mfma_f32_16x16x32_bf16 v[44:47], v[160:163], v[184:187], v[44:47]
	v_mfma_f32_16x16x32_bf16 v[40:43], v[168:171], v[184:187], v[40:43]
	v_mfma_f32_16x16x32_bf16 v[28:31], v[160:163], v[216:219], v[28:31]
	v_mfma_f32_16x16x32_bf16 v[24:27], v[168:171], v[216:219], v[24:27]
	v_mfma_f32_16x16x32_bf16 v[12:15], v[160:163], v[224:227], v[12:15]
	v_mfma_f32_16x16x32_bf16 v[8:11], v[168:171], v[224:227], v[8:11]
	s_barrier
	s_add_u32 s22, s22, 0x40080
	s_addc_u32 s23, s23, 0
	s_add_i32 s24, s24, s29
	s_mov_b32 m0, s24
	s_nop 0
	global_load_lds_dwordx4 v132, s[22:23]
	s_add_i32 m0, s24, 0x2000
	s_nop 0
	global_load_lds_dwordx4 v128, s[22:23]
	v_add_u32_e32 v168, 0x10000, v154
	ds_read_b128 v[156:159], v168
	ds_read_b128 v[160:163], v168 offset:1024
	ds_read_b128 v[164:167], v168 offset:2048
	ds_read_b128 v[168:171], v168 offset:3072
	s_waitcnt vmcnt(10)
	s_barrier
	v_mfma_f32_16x16x32_bf16 v[52:55], v[228:231], v[172:175], v[52:55]
	v_mfma_f32_16x16x32_bf16 v[48:51], v[236:239], v[172:175], v[48:51]
	v_mfma_f32_16x16x32_bf16 v[36:39], v[228:231], v[180:183], v[36:39]
	v_mfma_f32_16x16x32_bf16 v[32:35], v[236:239], v[180:183], v[32:35]
	v_mfma_f32_16x16x32_bf16 v[20:23], v[228:231], v[188:191], v[20:23]
	v_mfma_f32_16x16x32_bf16 v[16:19], v[236:239], v[188:191], v[16:19]
	v_mfma_f32_16x16x32_bf16 v[4:7], v[228:231], v[220:223], v[4:7]
	v_mfma_f32_16x16x32_bf16 v[0:3], v[236:239], v[220:223], v[0:3]
	v_mfma_f32_16x16x32_bf16 v[52:55], v[232:235], v[176:179], v[52:55]
	v_mfma_f32_16x16x32_bf16 v[48:51], v[240:243], v[176:179], v[48:51]
	v_mfma_f32_16x16x32_bf16 v[36:39], v[232:235], v[184:187], v[36:39]
	v_mfma_f32_16x16x32_bf16 v[32:35], v[240:243], v[184:187], v[32:35]
	v_mfma_f32_16x16x32_bf16 v[20:23], v[232:235], v[216:219], v[20:23]
	v_mfma_f32_16x16x32_bf16 v[16:19], v[240:243], v[216:219], v[16:19]
	v_mfma_f32_16x16x32_bf16 v[4:7], v[232:235], v[224:227], v[4:7]
	v_mfma_f32_16x16x32_bf16 v[0:3], v[240:243], v[224:227], v[0:3]
	s_add_i32 s46, s46, 2
	s_add_u32 s18, s18, 0x100
	s_addc_u32 s19, s19, 0
	s_add_u32 s44, s44, 0x100
	s_addc_u32 s45, s45, 0
	s_cmp_gt_u32 s46, 13
	s_barrier
	s_cbranch_scc0 .LBB0_1104
	s_setprio 0
	s_waitcnt lgkmcnt(0)
	v_mov_b32_e32 v153, v135
	s_mov_b64 s[18:19], s[0:1]
	s_load_dwordx2 s[18:19], s[18:19], 0x88
	s_nop 0
	v_readfirstlane_b32 s7, v153
	s_ashr_i32 s9, s7, 2
	s_lshr_b32 s7, s7, 1
	s_lshl_b32 s22, s41, 7
	s_and_b32 s7, s7, 0x60
	s_andn2_b32 s9, s9, 63
	s_or_b32 s7, s7, s22
	v_lshrrev_b32_e32 v152, 1, v153
	v_and_or_b32 v152, v152, 24, s7
	v_and_or_b32 v153, v153, 15, s9
	v_lshl_add_u32 v156, s16, 8, v153
	v_ashrrev_i32_e32 v153, 31, v152
	v_mov_b32_e32 v168, 0xbfb8aa3b
	v_mov_b32_e32 v169, 0xbfb8aa3b
	v_mov_b32_e32 v170, 1.0
	v_mov_b32_e32 v171, 1.0
	v_pk_mul_f32 v[160:161], v[124:125], v[168:169]
	v_pk_mul_f32 v[162:163], v[126:127], v[168:169]
	v_pk_mul_f32 v[164:165], v[116:117], v[168:169]
	v_pk_mul_f32 v[166:167], v[118:119], v[168:169]
	v_exp_f32_e32 v160, v160
	v_exp_f32_e32 v161, v161
	v_exp_f32_e32 v162, v162
	v_exp_f32_e32 v163, v163
	v_exp_f32_e32 v164, v164
	v_exp_f32_e32 v165, v165
	v_exp_f32_e32 v166, v166
	v_exp_f32_e32 v167, v167
	s_waitcnt lgkmcnt(0)
	v_lshl_add_u64 v[152:153], v[152:153], 1, s[18:19]
	s_mov_b64 s[18:19], 0xa2a4400
	v_lshl_add_u64 v[152:153], v[152:153], 0, s[18:19]
	s_and_b64 vcc, exec, s[4:5]
	s_mov_b32 s41, s6
	s_mov_b32 s16, s8
	s_mov_b64 s[22:23], s[12:13]
	v_pk_add_f32 v[160:161], v[160:161], v[170:171]
	v_pk_add_f32 v[162:163], v[162:163], v[170:171]
	v_pk_add_f32 v[164:165], v[164:165], v[170:171]
	v_pk_add_f32 v[166:167], v[166:167], v[170:171]
	v_rcp_f32_e32 v160, v160
	v_rcp_f32_e32 v161, v161
	v_rcp_f32_e32 v162, v162
	v_rcp_f32_e32 v163, v163
	v_rcp_f32_e32 v164, v164
	v_rcp_f32_e32 v165, v165
	v_rcp_f32_e32 v166, v166
	v_rcp_f32_e32 v167, v167
	v_mov_b32_e32 v158, v156
	v_mad_i64_i32 v[158:159], s[18:19], v158, s73, v[152:153]
	v_pk_mul_f32 v[124:125], v[124:125], v[160:161]
	v_pk_mul_f32 v[126:127], v[126:127], v[162:163]
	v_pk_mul_f32 v[116:117], v[116:117], v[164:165]
	v_pk_mul_f32 v[118:119], v[118:119], v[166:167]
	v_pk_mul_f32 v[120:121], v[120:121], v[124:125]
	v_pk_mul_f32 v[122:123], v[122:123], v[126:127]
	v_pk_mul_f32 v[112:113], v[112:113], v[116:117]
	v_pk_mul_f32 v[114:115], v[114:115], v[118:119]
	v_cvt_pk_bf16_f32 v120, v120, v121
	v_cvt_pk_bf16_f32 v121, v122, v123
	v_cvt_pk_bf16_f32 v122, v112, v113
	v_cvt_pk_bf16_f32 v123, v114, v115
	global_store_dwordx4 v[158:159], v[120:123], off sc1
	v_pk_mul_f32 v[160:161], v[108:109], v[168:169]
	v_pk_mul_f32 v[162:163], v[110:111], v[168:169]
	v_pk_mul_f32 v[164:165], v[100:101], v[168:169]
	v_pk_mul_f32 v[166:167], v[102:103], v[168:169]
	v_exp_f32_e32 v160, v160
	v_exp_f32_e32 v161, v161
	v_exp_f32_e32 v162, v162
	v_exp_f32_e32 v163, v163
	v_exp_f32_e32 v164, v164
	v_exp_f32_e32 v165, v165
	v_exp_f32_e32 v166, v166
	v_exp_f32_e32 v167, v167
	v_pk_add_f32 v[160:161], v[160:161], v[170:171]
	v_pk_add_f32 v[162:163], v[162:163], v[170:171]
	v_pk_add_f32 v[164:165], v[164:165], v[170:171]
	v_pk_add_f32 v[166:167], v[166:167], v[170:171]
	v_rcp_f32_e32 v160, v160
	v_rcp_f32_e32 v161, v161
	v_rcp_f32_e32 v162, v162
	v_rcp_f32_e32 v163, v163
	v_rcp_f32_e32 v164, v164
	v_rcp_f32_e32 v165, v165
	v_rcp_f32_e32 v166, v166
	v_rcp_f32_e32 v167, v167
	v_add_u32_e32 v158, 0x10, v156
	v_mad_i64_i32 v[158:159], s[18:19], v158, s73, v[152:153]
	v_pk_mul_f32 v[108:109], v[108:109], v[160:161]
	v_pk_mul_f32 v[110:111], v[110:111], v[162:163]
	v_pk_mul_f32 v[100:101], v[100:101], v[164:165]
	v_pk_mul_f32 v[102:103], v[102:103], v[166:167]
	v_pk_mul_f32 v[104:105], v[104:105], v[108:109]
	v_pk_mul_f32 v[106:107], v[106:107], v[110:111]
	v_pk_mul_f32 v[96:97], v[96:97], v[100:101]
	v_pk_mul_f32 v[98:99], v[98:99], v[102:103]
	v_cvt_pk_bf16_f32 v104, v104, v105
	v_cvt_pk_bf16_f32 v105, v106, v107
	v_cvt_pk_bf16_f32 v106, v96, v97
	v_cvt_pk_bf16_f32 v107, v98, v99
	global_store_dwordx4 v[158:159], v[104:107], off sc1
	v_pk_mul_f32 v[160:161], v[92:93], v[168:169]
	v_pk_mul_f32 v[162:163], v[94:95], v[168:169]
	v_pk_mul_f32 v[164:165], v[84:85], v[168:169]
	v_pk_mul_f32 v[166:167], v[86:87], v[168:169]
	v_exp_f32_e32 v160, v160
	v_exp_f32_e32 v161, v161
	v_exp_f32_e32 v162, v162
	v_exp_f32_e32 v163, v163
	v_exp_f32_e32 v164, v164
	v_exp_f32_e32 v165, v165
	v_exp_f32_e32 v166, v166
	v_exp_f32_e32 v167, v167
	v_pk_add_f32 v[160:161], v[160:161], v[170:171]
	v_pk_add_f32 v[162:163], v[162:163], v[170:171]
	v_pk_add_f32 v[164:165], v[164:165], v[170:171]
	v_pk_add_f32 v[166:167], v[166:167], v[170:171]
	v_rcp_f32_e32 v160, v160
	v_rcp_f32_e32 v161, v161
	v_rcp_f32_e32 v162, v162
	v_rcp_f32_e32 v163, v163
	v_rcp_f32_e32 v164, v164
	v_rcp_f32_e32 v165, v165
	v_rcp_f32_e32 v166, v166
	v_rcp_f32_e32 v167, v167
	v_add_u32_e32 v158, 0x20, v156
	v_mad_i64_i32 v[158:159], s[18:19], v158, s73, v[152:153]
	v_pk_mul_f32 v[92:93], v[92:93], v[160:161]
	v_pk_mul_f32 v[94:95], v[94:95], v[162:163]
	v_pk_mul_f32 v[84:85], v[84:85], v[164:165]
	v_pk_mul_f32 v[86:87], v[86:87], v[166:167]
	v_pk_mul_f32 v[88:89], v[88:89], v[92:93]
	v_pk_mul_f32 v[90:91], v[90:91], v[94:95]
	v_pk_mul_f32 v[80:81], v[80:81], v[84:85]
	v_pk_mul_f32 v[82:83], v[82:83], v[86:87]
	v_cvt_pk_bf16_f32 v88, v88, v89
	v_cvt_pk_bf16_f32 v89, v90, v91
	v_cvt_pk_bf16_f32 v90, v80, v81
	v_cvt_pk_bf16_f32 v91, v82, v83
	global_store_dwordx4 v[158:159], v[88:91], off sc1
	v_pk_mul_f32 v[160:161], v[76:77], v[168:169]
	v_pk_mul_f32 v[162:163], v[78:79], v[168:169]
	v_pk_mul_f32 v[164:165], v[68:69], v[168:169]
	v_pk_mul_f32 v[166:167], v[70:71], v[168:169]
	v_exp_f32_e32 v160, v160
	v_exp_f32_e32 v161, v161
	v_exp_f32_e32 v162, v162
	v_exp_f32_e32 v163, v163
	v_exp_f32_e32 v164, v164
	v_exp_f32_e32 v165, v165
	v_exp_f32_e32 v166, v166
	v_exp_f32_e32 v167, v167
	v_pk_add_f32 v[160:161], v[160:161], v[170:171]
	v_pk_add_f32 v[162:163], v[162:163], v[170:171]
	v_pk_add_f32 v[164:165], v[164:165], v[170:171]
	v_pk_add_f32 v[166:167], v[166:167], v[170:171]
	v_rcp_f32_e32 v160, v160
	v_rcp_f32_e32 v161, v161
	v_rcp_f32_e32 v162, v162
	v_rcp_f32_e32 v163, v163
	v_rcp_f32_e32 v164, v164
	v_rcp_f32_e32 v165, v165
	v_rcp_f32_e32 v166, v166
	v_rcp_f32_e32 v167, v167
	v_add_u32_e32 v158, 0x30, v156
	v_mad_i64_i32 v[158:159], s[18:19], v158, s73, v[152:153]
	v_pk_mul_f32 v[76:77], v[76:77], v[160:161]
	v_pk_mul_f32 v[78:79], v[78:79], v[162:163]
	v_pk_mul_f32 v[68:69], v[68:69], v[164:165]
	v_pk_mul_f32 v[70:71], v[70:71], v[166:167]
	v_pk_mul_f32 v[72:73], v[72:73], v[76:77]
	v_pk_mul_f32 v[74:75], v[74:75], v[78:79]
	v_pk_mul_f32 v[64:65], v[64:65], v[68:69]
	v_pk_mul_f32 v[66:67], v[66:67], v[70:71]
	v_cvt_pk_bf16_f32 v72, v72, v73
	v_cvt_pk_bf16_f32 v73, v74, v75
	v_cvt_pk_bf16_f32 v74, v64, v65
	v_cvt_pk_bf16_f32 v75, v66, v67
	global_store_dwordx4 v[158:159], v[72:75], off sc1
	v_pk_mul_f32 v[160:161], v[60:61], v[168:169]
	v_pk_mul_f32 v[162:163], v[62:63], v[168:169]
	v_pk_mul_f32 v[164:165], v[52:53], v[168:169]
	v_pk_mul_f32 v[166:167], v[54:55], v[168:169]
	v_exp_f32_e32 v160, v160
	v_exp_f32_e32 v161, v161
	v_exp_f32_e32 v162, v162
	v_exp_f32_e32 v163, v163
	v_exp_f32_e32 v164, v164
	v_exp_f32_e32 v165, v165
	v_exp_f32_e32 v166, v166
	v_exp_f32_e32 v167, v167
	v_pk_add_f32 v[160:161], v[160:161], v[170:171]
	v_pk_add_f32 v[162:163], v[162:163], v[170:171]
	v_pk_add_f32 v[164:165], v[164:165], v[170:171]
	v_pk_add_f32 v[166:167], v[166:167], v[170:171]
	v_rcp_f32_e32 v160, v160
	v_rcp_f32_e32 v161, v161
	v_rcp_f32_e32 v162, v162
	v_rcp_f32_e32 v163, v163
	v_rcp_f32_e32 v164, v164
	v_rcp_f32_e32 v165, v165
	v_rcp_f32_e32 v166, v166
	v_rcp_f32_e32 v167, v167
	v_add_u32_e32 v158, 0x80, v156
	v_mad_i64_i32 v[158:159], s[18:19], v158, s73, v[152:153]
	v_pk_mul_f32 v[60:61], v[60:61], v[160:161]
	v_pk_mul_f32 v[62:63], v[62:63], v[162:163]
	v_pk_mul_f32 v[52:53], v[52:53], v[164:165]
	v_pk_mul_f32 v[54:55], v[54:55], v[166:167]
	v_pk_mul_f32 v[56:57], v[56:57], v[60:61]
	v_pk_mul_f32 v[58:59], v[58:59], v[62:63]
	v_pk_mul_f32 v[48:49], v[48:49], v[52:53]
	v_pk_mul_f32 v[50:51], v[50:51], v[54:55]
	v_cvt_pk_bf16_f32 v56, v56, v57
	v_cvt_pk_bf16_f32 v57, v58, v59
	v_cvt_pk_bf16_f32 v58, v48, v49
	v_cvt_pk_bf16_f32 v59, v50, v51
	global_store_dwordx4 v[158:159], v[56:59], off sc1
	v_pk_mul_f32 v[160:161], v[44:45], v[168:169]
	v_pk_mul_f32 v[162:163], v[46:47], v[168:169]
	v_pk_mul_f32 v[164:165], v[36:37], v[168:169]
	v_pk_mul_f32 v[166:167], v[38:39], v[168:169]
	v_exp_f32_e32 v160, v160
	v_exp_f32_e32 v161, v161
	v_exp_f32_e32 v162, v162
	v_exp_f32_e32 v163, v163
	v_exp_f32_e32 v164, v164
	v_exp_f32_e32 v165, v165
	v_exp_f32_e32 v166, v166
	v_exp_f32_e32 v167, v167
	v_pk_add_f32 v[160:161], v[160:161], v[170:171]
	v_pk_add_f32 v[162:163], v[162:163], v[170:171]
	v_pk_add_f32 v[164:165], v[164:165], v[170:171]
	v_pk_add_f32 v[166:167], v[166:167], v[170:171]
	v_rcp_f32_e32 v160, v160
	v_rcp_f32_e32 v161, v161
	v_rcp_f32_e32 v162, v162
	v_rcp_f32_e32 v163, v163
	v_rcp_f32_e32 v164, v164
	v_rcp_f32_e32 v165, v165
	v_rcp_f32_e32 v166, v166
	v_rcp_f32_e32 v167, v167
	v_add_u32_e32 v158, 0x90, v156
	v_mad_i64_i32 v[158:159], s[18:19], v158, s73, v[152:153]
	v_pk_mul_f32 v[44:45], v[44:45], v[160:161]
	v_pk_mul_f32 v[46:47], v[46:47], v[162:163]
	v_pk_mul_f32 v[36:37], v[36:37], v[164:165]
	v_pk_mul_f32 v[38:39], v[38:39], v[166:167]
	v_pk_mul_f32 v[40:41], v[40:41], v[44:45]
	v_pk_mul_f32 v[42:43], v[42:43], v[46:47]
	v_pk_mul_f32 v[32:33], v[32:33], v[36:37]
	v_pk_mul_f32 v[34:35], v[34:35], v[38:39]
	v_cvt_pk_bf16_f32 v40, v40, v41
	v_cvt_pk_bf16_f32 v41, v42, v43
	v_cvt_pk_bf16_f32 v42, v32, v33
	v_cvt_pk_bf16_f32 v43, v34, v35
	global_store_dwordx4 v[158:159], v[40:43], off sc1
	v_pk_mul_f32 v[160:161], v[28:29], v[168:169]
	v_pk_mul_f32 v[162:163], v[30:31], v[168:169]
	v_pk_mul_f32 v[164:165], v[20:21], v[168:169]
	v_pk_mul_f32 v[166:167], v[22:23], v[168:169]
	v_exp_f32_e32 v160, v160
	v_exp_f32_e32 v161, v161
	v_exp_f32_e32 v162, v162
	v_exp_f32_e32 v163, v163
	v_exp_f32_e32 v164, v164
	v_exp_f32_e32 v165, v165
	v_exp_f32_e32 v166, v166
	v_exp_f32_e32 v167, v167
	v_pk_add_f32 v[160:161], v[160:161], v[170:171]
	v_pk_add_f32 v[162:163], v[162:163], v[170:171]
	v_pk_add_f32 v[164:165], v[164:165], v[170:171]
	v_pk_add_f32 v[166:167], v[166:167], v[170:171]
	v_rcp_f32_e32 v160, v160
	v_rcp_f32_e32 v161, v161
	v_rcp_f32_e32 v162, v162
	v_rcp_f32_e32 v163, v163
	v_rcp_f32_e32 v164, v164
	v_rcp_f32_e32 v165, v165
	v_rcp_f32_e32 v166, v166
	v_rcp_f32_e32 v167, v167
	v_add_u32_e32 v158, 0xa0, v156
	v_mad_i64_i32 v[158:159], s[18:19], v158, s73, v[152:153]
	v_pk_mul_f32 v[28:29], v[28:29], v[160:161]
	v_pk_mul_f32 v[30:31], v[30:31], v[162:163]
	v_pk_mul_f32 v[20:21], v[20:21], v[164:165]
	v_pk_mul_f32 v[22:23], v[22:23], v[166:167]
	v_pk_mul_f32 v[24:25], v[24:25], v[28:29]
	v_pk_mul_f32 v[26:27], v[26:27], v[30:31]
	v_pk_mul_f32 v[16:17], v[16:17], v[20:21]
	v_pk_mul_f32 v[18:19], v[18:19], v[22:23]
	v_cvt_pk_bf16_f32 v24, v24, v25
	v_cvt_pk_bf16_f32 v25, v26, v27
	v_cvt_pk_bf16_f32 v26, v16, v17
	v_cvt_pk_bf16_f32 v27, v18, v19
	global_store_dwordx4 v[158:159], v[24:27], off sc1
	v_pk_mul_f32 v[160:161], v[12:13], v[168:169]
	v_pk_mul_f32 v[162:163], v[14:15], v[168:169]
	v_pk_mul_f32 v[164:165], v[4:5], v[168:169]
	v_pk_mul_f32 v[166:167], v[6:7], v[168:169]
	v_exp_f32_e32 v160, v160
	v_exp_f32_e32 v161, v161
	v_exp_f32_e32 v162, v162
	v_exp_f32_e32 v163, v163
	v_exp_f32_e32 v164, v164
	v_exp_f32_e32 v165, v165
	v_exp_f32_e32 v166, v166
	v_exp_f32_e32 v167, v167
	v_pk_add_f32 v[160:161], v[160:161], v[170:171]
	v_pk_add_f32 v[162:163], v[162:163], v[170:171]
	v_pk_add_f32 v[164:165], v[164:165], v[170:171]
	v_pk_add_f32 v[166:167], v[166:167], v[170:171]
	v_rcp_f32_e32 v160, v160
	v_rcp_f32_e32 v161, v161
	v_rcp_f32_e32 v162, v162
	v_rcp_f32_e32 v163, v163
	v_rcp_f32_e32 v164, v164
	v_rcp_f32_e32 v165, v165
	v_rcp_f32_e32 v166, v166
	v_rcp_f32_e32 v167, v167
	v_add_u32_e32 v158, 0xb0, v156
	v_mad_i64_i32 v[158:159], s[18:19], v158, s73, v[152:153]
	v_pk_mul_f32 v[12:13], v[12:13], v[160:161]
	v_pk_mul_f32 v[14:15], v[14:15], v[162:163]
	v_pk_mul_f32 v[4:5], v[4:5], v[164:165]
	v_pk_mul_f32 v[6:7], v[6:7], v[166:167]
	v_pk_mul_f32 v[8:9], v[8:9], v[12:13]
	v_pk_mul_f32 v[10:11], v[10:11], v[14:15]
	v_pk_mul_f32 v[0:1], v[0:1], v[4:5]
	v_pk_mul_f32 v[2:3], v[2:3], v[6:7]
	v_cvt_pk_bf16_f32 v8, v8, v9
	v_cvt_pk_bf16_f32 v9, v10, v11
	v_cvt_pk_bf16_f32 v10, v0, v1
	v_cvt_pk_bf16_f32 v11, v2, v3
	global_store_dwordx4 v[158:159], v[8:11], off sc1
	s_mov_b64 s[18:19], s[10:11]
	s_cbranch_vccz .LBB0_1101
	s_waitcnt vmcnt(0)
	s_cmpk_gt_u32 s14, 0xff
	s_cbranch_scc1 .LBB0_1108
	s_barrier

.LBB0_1233:
	s_add_u32 s8, s12, 0x80
	s_addc_u32 s9, s13, 0
	s_add_u32 s38, s10, 0x100
	v_mov_b32_e32 v0, 0
	s_addc_u32 s39, s11, 0
	s_mov_b32 s10, 0
	v_mov_b32_e32 v1, v0
	v_mov_b64_e32 v[2:3], 0
	v_mov_b64_e32 v[4:5], 0
	v_mov_b64_e32 v[6:7], 0
	v_mov_b64_e32 v[8:9], 0
	v_mov_b64_e32 v[10:11], 0
	v_mov_b64_e32 v[12:13], 0
	v_mov_b64_e32 v[14:15], 0
	v_mov_b64_e32 v[16:17], 0
	v_mov_b64_e32 v[18:19], 0
	v_mov_b64_e32 v[20:21], 0
	v_mov_b64_e32 v[22:23], 0
	v_mov_b64_e32 v[24:25], 0
	v_mov_b64_e32 v[26:27], 0
	v_mov_b64_e32 v[28:29], 0
	v_mov_b64_e32 v[30:31], 0
	v_mov_b64_e32 v[32:33], 0
	v_mov_b64_e32 v[34:35], 0
	v_mov_b64_e32 v[36:37], 0
	v_mov_b64_e32 v[38:39], 0
	v_mov_b64_e32 v[40:41], 0
	v_mov_b64_e32 v[42:43], 0
	v_mov_b64_e32 v[44:45], 0
	v_mov_b64_e32 v[46:47], 0
	v_mov_b64_e32 v[48:49], 0
	v_mov_b64_e32 v[50:51], 0
	v_mov_b64_e32 v[52:53], 0
	v_mov_b64_e32 v[54:55], 0
	v_mov_b64_e32 v[56:57], 0
	v_mov_b64_e32 v[58:59], 0
	v_mov_b64_e32 v[60:61], 0
	v_mov_b64_e32 v[62:63], 0
	v_mov_b64_e32 v[64:65], 0
	v_mov_b64_e32 v[66:67], 0
	v_mov_b64_e32 v[68:69], 0
	v_mov_b64_e32 v[70:71], 0
	v_mov_b64_e32 v[72:73], 0
	v_mov_b64_e32 v[74:75], 0
	v_mov_b64_e32 v[76:77], 0
	v_mov_b64_e32 v[78:79], 0
	v_mov_b64_e32 v[80:81], 0
	v_mov_b64_e32 v[82:83], 0
	v_mov_b64_e32 v[84:85], 0
	v_mov_b64_e32 v[86:87], 0
	v_mov_b64_e32 v[88:89], 0
	v_mov_b64_e32 v[90:91], 0
	v_mov_b64_e32 v[92:93], 0
	v_mov_b64_e32 v[94:95], 0
	v_mov_b64_e32 v[96:97], 0
	v_mov_b64_e32 v[98:99], 0
	v_mov_b64_e32 v[100:101], 0
	v_mov_b64_e32 v[102:103], 0
	v_mov_b64_e32 v[104:105], 0
	v_mov_b64_e32 v[106:107], 0
	v_mov_b64_e32 v[108:109], 0
	v_mov_b64_e32 v[110:111], 0
	v_mov_b64_e32 v[112:113], 0
	v_mov_b64_e32 v[114:115], 0
	v_mov_b64_e32 v[116:117], 0
	v_mov_b64_e32 v[118:119], 0
	v_mov_b64_e32 v[120:121], 0
	v_mov_b64_e32 v[122:123], 0
	v_mov_b64_e32 v[124:125], 0
	v_mov_b64_e32 v[126:127], 0
	v_add_u32_e32 v168, 0x10000, v154
	ds_read_b128 v[156:159], v168
	ds_read_b128 v[160:163], v168 offset:1024
	ds_read_b128 v[164:167], v168 offset:2048
	ds_read_b128 v[168:171], v168 offset:3072
	v_readfirstlane_b32 s98, v135
	s_cmpk_gt_u32 s98, 0xff
	s_cbranch_scc0 .Lkprio_3
	s_setprio 1
.Lkprio_3:
.LBB0_1234:
	s_add_i32 s40, s10, 2
	s_add_u32 s12, s8, 0x80
	s_addc_u32 s11, s9, 0
	s_add_i32 s41, 0, 0x10000
	s_cmp_eq_u32 s29, s10
	s_cselect_b32 s10, s2, s12
	s_cselect_b32 s11, s3, s11
	s_cselect_b32 s13, s7, s39
	s_cselect_b32 s12, s6, s38
	s_add_i32 m0, s22, 0xc000
	ds_read_b128 v[172:175], v155
	ds_read_b128 v[180:183], v155 offset:2048
	ds_read_b128 v[188:191], v155 offset:4096
	ds_read_b128 v[220:223], v155 offset:6144
	ds_read_b128 v[176:179], v155 offset:1024
	ds_read_b128 v[184:187], v155 offset:3072
	ds_read_b128 v[216:219], v155 offset:5120
	ds_read_b128 v[224:227], v155 offset:7168
	global_load_lds_dwordx4 v130, s[8:9]
	s_add_i32 m0, s22, 0xe000
	s_nop 0
	global_load_lds_dwordx4 v150, s[8:9]
	s_waitcnt lgkmcnt(8)
	s_waitcnt vmcnt(10)
	s_barrier
	s_waitcnt lgkmcnt(4)
	v_mfma_f32_16x16x32_bf16 v[124:127], v[156:159], v[172:175], v[124:127]
	v_mfma_f32_16x16x32_bf16 v[120:123], v[164:167], v[172:175], v[120:123]
	v_mfma_f32_16x16x32_bf16 v[116:119], v[156:159], v[180:183], v[116:119]
	v_mfma_f32_16x16x32_bf16 v[108:111], v[164:167], v[180:183], v[108:111]
	v_mfma_f32_16x16x32_bf16 v[100:103], v[156:159], v[188:191], v[100:103]
	v_mfma_f32_16x16x32_bf16 v[92:95], v[164:167], v[188:191], v[92:95]
	v_mfma_f32_16x16x32_bf16 v[84:87], v[156:159], v[220:223], v[84:87]
	v_mfma_f32_16x16x32_bf16 v[76:79], v[164:167], v[220:223], v[76:79]
	s_waitcnt lgkmcnt(0)
	v_mfma_f32_16x16x32_bf16 v[124:127], v[160:163], v[176:179], v[124:127]
	v_mfma_f32_16x16x32_bf16 v[120:123], v[168:171], v[176:179], v[120:123]
	v_mfma_f32_16x16x32_bf16 v[116:119], v[160:163], v[184:187], v[116:119]
	v_mfma_f32_16x16x32_bf16 v[108:111], v[168:171], v[184:187], v[108:111]
	v_mfma_f32_16x16x32_bf16 v[100:103], v[160:163], v[216:219], v[100:103]
	v_mfma_f32_16x16x32_bf16 v[92:95], v[168:171], v[216:219], v[92:95]
	v_mfma_f32_16x16x32_bf16 v[84:87], v[160:163], v[224:227], v[84:87]
	v_mfma_f32_16x16x32_bf16 v[76:79], v[168:171], v[224:227], v[76:79]
	s_barrier
	s_add_i32 s42, 0, 0x14000
	v_add_u32_e32 v152, s42, v154
	s_add_i32 s41, s41, s19
	ds_read_b128 v[228:231], v152
	ds_read_b128 v[236:239], v152 offset:2048
	ds_read_b128 v[232:235], v152 offset:1024
	ds_read_b128 v[240:243], v152 offset:3072
	v_lshl_add_u64 v[152:153], s[12:13], 0, v[132:133]
	s_mov_b32 m0, s41
	v_lshl_add_u64 v[244:245], s[12:13], 0, v[128:129]
	global_load_lds_dwordx4 v132, s[12:13]
	s_add_i32 m0, s41, 0x2000
	s_nop 0
	global_load_lds_dwordx4 v128, s[12:13]
	s_waitcnt vmcnt(10)
	s_barrier
	s_waitcnt lgkmcnt(2)
	v_mfma_f32_16x16x32_bf16 v[112:115], v[228:231], v[172:175], v[112:115]
	v_mfma_f32_16x16x32_bf16 v[104:107], v[236:239], v[172:175], v[104:107]
	v_mfma_f32_16x16x32_bf16 v[96:99], v[228:231], v[180:183], v[96:99]
	v_mfma_f32_16x16x32_bf16 v[88:91], v[236:239], v[180:183], v[88:91]
	v_mfma_f32_16x16x32_bf16 v[80:83], v[228:231], v[188:191], v[80:83]
	v_mfma_f32_16x16x32_bf16 v[72:75], v[236:239], v[188:191], v[72:75]
	v_mfma_f32_16x16x32_bf16 v[68:71], v[228:231], v[220:223], v[68:71]
	v_mfma_f32_16x16x32_bf16 v[64:67], v[236:239], v[220:223], v[64:67]
	s_waitcnt lgkmcnt(0)
	v_mfma_f32_16x16x32_bf16 v[112:115], v[232:235], v[176:179], v[112:115]
	v_mfma_f32_16x16x32_bf16 v[104:107], v[240:243], v[176:179], v[104:107]
	v_mfma_f32_16x16x32_bf16 v[96:99], v[232:235], v[184:187], v[96:99]
	v_mfma_f32_16x16x32_bf16 v[88:91], v[240:243], v[184:187], v[88:91]
	v_mfma_f32_16x16x32_bf16 v[80:83], v[232:235], v[216:219], v[80:83]
	v_mfma_f32_16x16x32_bf16 v[72:75], v[240:243], v[216:219], v[72:75]
	v_mfma_f32_16x16x32_bf16 v[68:71], v[232:235], v[224:227], v[68:71]
	v_mfma_f32_16x16x32_bf16 v[64:67], v[240:243], v[224:227], v[64:67]
	s_mov_b32 m0, s22
	v_lshl_add_u64 v[246:247], s[10:11], 0, v[132:133]
	s_barrier
	ds_read_b128 v[172:175], v155 offset:16384
	ds_read_b128 v[180:183], v155 offset:18432
	ds_read_b128 v[188:191], v155 offset:20480
	ds_read_b128 v[220:223], v155 offset:22528
	ds_read_b128 v[176:179], v155 offset:17408
	ds_read_b128 v[184:187], v155 offset:19456
	ds_read_b128 v[216:219], v155 offset:21504
	ds_read_b128 v[224:227], v155 offset:23552
	global_load_lds_dwordx4 v132, s[10:11]
	v_lshl_add_u64 v[248:249], s[10:11], 0, v[128:129]
	s_mov_b32 m0, s23
	s_nop 0
	global_load_lds_dwordx4 v128, s[10:11]
	s_waitcnt vmcnt(10)
	s_barrier
	s_waitcnt lgkmcnt(4)
	v_mfma_f32_16x16x32_bf16 v[60:63], v[156:159], v[172:175], v[60:63]
	v_mfma_f32_16x16x32_bf16 v[56:59], v[164:167], v[172:175], v[56:59]
	v_mfma_f32_16x16x32_bf16 v[52:55], v[156:159], v[180:183], v[52:55]
	v_mfma_f32_16x16x32_bf16 v[44:47], v[164:167], v[180:183], v[44:47]
	v_mfma_f32_16x16x32_bf16 v[36:39], v[156:159], v[188:191], v[36:39]
	v_mfma_f32_16x16x32_bf16 v[28:31], v[164:167], v[188:191], v[28:31]
	v_mfma_f32_16x16x32_bf16 v[20:23], v[156:159], v[220:223], v[20:23]
	v_mfma_f32_16x16x32_bf16 v[12:15], v[164:167], v[220:223], v[12:15]
	s_waitcnt lgkmcnt(0)
	v_mfma_f32_16x16x32_bf16 v[60:63], v[160:163], v[176:179], v[60:63]
	v_mfma_f32_16x16x32_bf16 v[56:59], v[168:171], v[176:179], v[56:59]
	v_mfma_f32_16x16x32_bf16 v[52:55], v[160:163], v[184:187], v[52:55]
	v_mfma_f32_16x16x32_bf16 v[44:47], v[168:171], v[184:187], v[44:47]
	v_mfma_f32_16x16x32_bf16 v[36:39], v[160:163], v[216:219], v[36:39]
	v_mfma_f32_16x16x32_bf16 v[28:31], v[168:171], v[216:219], v[28:31]
	v_mfma_f32_16x16x32_bf16 v[20:23], v[160:163], v[224:227], v[20:23]
	v_mfma_f32_16x16x32_bf16 v[12:15], v[168:171], v[224:227], v[12:15]
	s_barrier
	s_add_u32 s12, s12, s58
	s_addc_u32 s13, s13, 0
	s_add_i32 s41, s42, s19
	v_lshl_add_u64 v[250:251], s[12:13], 0, v[132:133]
	s_mov_b32 m0, s41
	v_lshl_add_u64 v[252:253], s[12:13], 0, v[128:129]
	global_load_lds_dwordx4 v132, s[12:13]
	s_add_i32 m0, s41, 0x2000
	s_nop 0
	global_load_lds_dwordx4 v128, s[12:13]
	v_add_u32_e32 v168, 0x18000, v154
	ds_read_b128 v[156:159], v168
	ds_read_b128 v[160:163], v168 offset:1024
	ds_read_b128 v[164:167], v168 offset:2048
	ds_read_b128 v[168:171], v168 offset:3072
	s_waitcnt vmcnt(10)
	s_barrier
	v_mfma_f32_16x16x32_bf16 v[48:51], v[228:231], v[172:175], v[48:51]
	v_mfma_f32_16x16x32_bf16 v[40:43], v[236:239], v[172:175], v[40:43]
	v_mfma_f32_16x16x32_bf16 v[32:35], v[228:231], v[180:183], v[32:35]
	v_mfma_f32_16x16x32_bf16 v[24:27], v[236:239], v[180:183], v[24:27]
	v_mfma_f32_16x16x32_bf16 v[16:19], v[228:231], v[188:191], v[16:19]
	v_mfma_f32_16x16x32_bf16 v[8:11], v[236:239], v[188:191], v[8:11]
	v_mfma_f32_16x16x32_bf16 v[4:7], v[228:231], v[220:223], v[4:7]
	v_mfma_f32_16x16x32_bf16 v[0:3], v[236:239], v[220:223], v[0:3]
	v_mfma_f32_16x16x32_bf16 v[48:51], v[232:235], v[176:179], v[48:51]
	v_mfma_f32_16x16x32_bf16 v[40:43], v[240:243], v[176:179], v[40:43]
	v_mfma_f32_16x16x32_bf16 v[32:35], v[232:235], v[184:187], v[32:35]
	v_mfma_f32_16x16x32_bf16 v[24:27], v[240:243], v[184:187], v[24:27]
	v_mfma_f32_16x16x32_bf16 v[16:19], v[232:235], v[216:219], v[16:19]
	v_mfma_f32_16x16x32_bf16 v[8:11], v[240:243], v[216:219], v[8:11]
	v_mfma_f32_16x16x32_bf16 v[4:7], v[232:235], v[224:227], v[4:7]
	v_mfma_f32_16x16x32_bf16 v[0:3], v[240:243], v[224:227], v[0:3]
	s_add_i32 s12, 0, 0x18000
	s_barrier
	s_add_u32 s10, s10, s58
	s_addc_u32 s11, s11, 0
	s_mov_b32 m0, s24
	ds_read_b128 v[172:175], v155 offset:32768
	ds_read_b128 v[180:183], v155 offset:34816
	ds_read_b128 v[188:191], v155 offset:36864
	ds_read_b128 v[220:223], v155 offset:38912
	ds_read_b128 v[176:179], v155 offset:33792
	ds_read_b128 v[184:187], v155 offset:35840
	ds_read_b128 v[216:219], v155 offset:37888
	ds_read_b128 v[224:227], v155 offset:39936
	global_load_lds_dwordx4 v132, s[10:11]
	s_mov_b32 m0, s25
	s_nop 0
	global_load_lds_dwordx4 v128, s[10:11]
	s_waitcnt lgkmcnt(8)
	s_waitcnt vmcnt(10)
	s_barrier
	s_waitcnt lgkmcnt(4)
	v_mfma_f32_16x16x32_bf16 v[124:127], v[156:159], v[172:175], v[124:127]
	v_mfma_f32_16x16x32_bf16 v[120:123], v[164:167], v[172:175], v[120:123]
	v_mfma_f32_16x16x32_bf16 v[116:119], v[156:159], v[180:183], v[116:119]
	v_mfma_f32_16x16x32_bf16 v[108:111], v[164:167], v[180:183], v[108:111]
	v_mfma_f32_16x16x32_bf16 v[100:103], v[156:159], v[188:191], v[100:103]
	v_mfma_f32_16x16x32_bf16 v[92:95], v[164:167], v[188:191], v[92:95]
	v_mfma_f32_16x16x32_bf16 v[84:87], v[156:159], v[220:223], v[84:87]
	v_mfma_f32_16x16x32_bf16 v[76:79], v[164:167], v[220:223], v[76:79]
	s_waitcnt lgkmcnt(0)
	v_mfma_f32_16x16x32_bf16 v[124:127], v[160:163], v[176:179], v[124:127]
	v_mfma_f32_16x16x32_bf16 v[120:123], v[168:171], v[176:179], v[120:123]
	v_mfma_f32_16x16x32_bf16 v[116:119], v[160:163], v[184:187], v[116:119]
	v_mfma_f32_16x16x32_bf16 v[108:111], v[168:171], v[184:187], v[108:111]
	v_mfma_f32_16x16x32_bf16 v[100:103], v[160:163], v[216:219], v[100:103]
	v_mfma_f32_16x16x32_bf16 v[92:95], v[168:171], v[216:219], v[92:95]
	v_mfma_f32_16x16x32_bf16 v[84:87], v[160:163], v[224:227], v[84:87]
	v_mfma_f32_16x16x32_bf16 v[76:79], v[168:171], v[224:227], v[76:79]
	s_barrier
	s_add_i32 s10, 0, 0x1c000
	s_add_i32 s11, s12, s19
	v_add_u32_e32 v200, s10, v154
	v_lshl_add_u64 v[152:153], v[152:153], 0, s[66:67]
	s_mov_b32 m0, s11
	ds_read_b128 v[228:231], v200
	ds_read_b128 v[236:239], v200 offset:2048
	ds_read_b128 v[232:235], v200 offset:1024
	ds_read_b128 v[240:243], v200 offset:3072
	global_load_lds_dwordx4 v[152:153], off
	v_lshl_add_u64 v[152:153], v[244:245], 0, s[66:67]
	s_add_i32 m0, s11, 0x2000
	s_nop 0
	global_load_lds_dwordx4 v[152:153], off
	s_waitcnt vmcnt(10)
	s_barrier
	s_waitcnt lgkmcnt(2)
	v_mfma_f32_16x16x32_bf16 v[112:115], v[228:231], v[172:175], v[112:115]
	v_mfma_f32_16x16x32_bf16 v[104:107], v[236:239], v[172:175], v[104:107]
	v_mfma_f32_16x16x32_bf16 v[96:99], v[228:231], v[180:183], v[96:99]
	v_mfma_f32_16x16x32_bf16 v[88:91], v[236:239], v[180:183], v[88:91]
	v_mfma_f32_16x16x32_bf16 v[80:83], v[228:231], v[188:191], v[80:83]
	v_mfma_f32_16x16x32_bf16 v[72:75], v[236:239], v[188:191], v[72:75]
	v_mfma_f32_16x16x32_bf16 v[68:71], v[228:231], v[220:223], v[68:71]
	v_mfma_f32_16x16x32_bf16 v[64:67], v[236:239], v[220:223], v[64:67]
	s_waitcnt lgkmcnt(0)
	v_mfma_f32_16x16x32_bf16 v[112:115], v[232:235], v[176:179], v[112:115]
	v_mfma_f32_16x16x32_bf16 v[104:107], v[240:243], v[176:179], v[104:107]
	v_mfma_f32_16x16x32_bf16 v[96:99], v[232:235], v[184:187], v[96:99]
	v_mfma_f32_16x16x32_bf16 v[88:91], v[240:243], v[184:187], v[88:91]
	v_mfma_f32_16x16x32_bf16 v[80:83], v[232:235], v[216:219], v[80:83]
	v_mfma_f32_16x16x32_bf16 v[72:75], v[240:243], v[216:219], v[72:75]
	v_mfma_f32_16x16x32_bf16 v[68:71], v[232:235], v[224:227], v[68:71]
	v_mfma_f32_16x16x32_bf16 v[64:67], v[240:243], v[224:227], v[64:67]
	s_mov_b32 m0, s26
	v_lshl_add_u64 v[152:153], v[246:247], 0, s[66:67]
	s_barrier
	ds_read_b128 v[172:175], v155 offset:49152
	ds_read_b128 v[180:183], v155 offset:51200
	ds_read_b128 v[188:191], v155 offset:53248
	ds_read_b128 v[220:223], v155 offset:55296
	ds_read_b128 v[176:179], v155 offset:50176
	ds_read_b128 v[184:187], v155 offset:52224
	ds_read_b128 v[216:219], v155 offset:54272
	ds_read_b128 v[224:227], v155 offset:56320
	global_load_lds_dwordx4 v[152:153], off
	v_lshl_add_u64 v[152:153], v[248:249], 0, s[66:67]
	s_mov_b32 m0, s27
	s_nop 0
	global_load_lds_dwordx4 v[152:153], off
	s_waitcnt vmcnt(10)
	s_barrier
	s_waitcnt lgkmcnt(4)
	v_mfma_f32_16x16x32_bf16 v[60:63], v[156:159], v[172:175], v[60:63]
	v_mfma_f32_16x16x32_bf16 v[56:59], v[164:167], v[172:175], v[56:59]
	v_mfma_f32_16x16x32_bf16 v[52:55], v[156:159], v[180:183], v[52:55]
	v_mfma_f32_16x16x32_bf16 v[44:47], v[164:167], v[180:183], v[44:47]
	v_mfma_f32_16x16x32_bf16 v[36:39], v[156:159], v[188:191], v[36:39]
	v_mfma_f32_16x16x32_bf16 v[28:31], v[164:167], v[188:191], v[28:31]
	v_mfma_f32_16x16x32_bf16 v[20:23], v[156:159], v[220:223], v[20:23]
	v_mfma_f32_16x16x32_bf16 v[12:15], v[164:167], v[220:223], v[12:15]
	s_waitcnt lgkmcnt(0)
	v_mfma_f32_16x16x32_bf16 v[60:63], v[160:163], v[176:179], v[60:63]
	v_mfma_f32_16x16x32_bf16 v[56:59], v[168:171], v[176:179], v[56:59]
	v_mfma_f32_16x16x32_bf16 v[52:55], v[160:163], v[184:187], v[52:55]
	v_mfma_f32_16x16x32_bf16 v[44:47], v[168:171], v[184:187], v[44:47]
	v_mfma_f32_16x16x32_bf16 v[36:39], v[160:163], v[216:219], v[36:39]
	v_mfma_f32_16x16x32_bf16 v[28:31], v[168:171], v[216:219], v[28:31]
	v_mfma_f32_16x16x32_bf16 v[20:23], v[160:163], v[224:227], v[20:23]
	v_mfma_f32_16x16x32_bf16 v[12:15], v[168:171], v[224:227], v[12:15]
	s_barrier
	s_add_i32 s10, s10, s19
	v_lshl_add_u64 v[152:153], v[250:251], 0, s[66:67]
	s_mov_b32 m0, s10
	s_nop 0
	global_load_lds_dwordx4 v[152:153], off
	v_lshl_add_u64 v[152:153], v[252:253], 0, s[66:67]
	s_add_i32 m0, s10, 0x2000
	s_nop 0
	global_load_lds_dwordx4 v[152:153], off
	v_add_u32_e32 v168, 0x10000, v154
	ds_read_b128 v[156:159], v168
	ds_read_b128 v[160:163], v168 offset:1024
	ds_read_b128 v[164:167], v168 offset:2048
	ds_read_b128 v[168:171], v168 offset:3072
	s_waitcnt vmcnt(10)
	s_barrier
	v_mfma_f32_16x16x32_bf16 v[48:51], v[228:231], v[172:175], v[48:51]
	v_mfma_f32_16x16x32_bf16 v[40:43], v[236:239], v[172:175], v[40:43]
	v_mfma_f32_16x16x32_bf16 v[32:35], v[228:231], v[180:183], v[32:35]
	v_mfma_f32_16x16x32_bf16 v[24:27], v[236:239], v[180:183], v[24:27]
	v_mfma_f32_16x16x32_bf16 v[16:19], v[228:231], v[188:191], v[16:19]
	v_mfma_f32_16x16x32_bf16 v[8:11], v[236:239], v[188:191], v[8:11]
	v_mfma_f32_16x16x32_bf16 v[4:7], v[228:231], v[220:223], v[4:7]
	v_mfma_f32_16x16x32_bf16 v[0:3], v[236:239], v[220:223], v[0:3]
	v_mfma_f32_16x16x32_bf16 v[48:51], v[232:235], v[176:179], v[48:51]
	v_mfma_f32_16x16x32_bf16 v[40:43], v[240:243], v[176:179], v[40:43]
	v_mfma_f32_16x16x32_bf16 v[32:35], v[232:235], v[184:187], v[32:35]
	v_mfma_f32_16x16x32_bf16 v[24:27], v[240:243], v[184:187], v[24:27]
	v_mfma_f32_16x16x32_bf16 v[16:19], v[232:235], v[216:219], v[16:19]
	v_mfma_f32_16x16x32_bf16 v[8:11], v[240:243], v[216:219], v[8:11]
	v_mfma_f32_16x16x32_bf16 v[4:7], v[232:235], v[224:227], v[4:7]
	v_mfma_f32_16x16x32_bf16 v[0:3], v[240:243], v[224:227], v[0:3]
	s_add_u32 s8, s8, 0x100
	s_addc_u32 s9, s9, 0
	s_add_u32 s38, s38, 0x100
	s_addc_u32 s39, s39, 0
	s_cmp_ge_u32 s40, s28
	s_mov_b32 s10, s40
	s_barrier
	s_cbranch_scc0 .LBB0_1234
	s_setprio 0
	s_waitcnt lgkmcnt(0)
	v_mov_b32_e32 v152, v135
	s_mov_b64 s[8:9], s[0:1]
	v_readfirstlane_b32 s10, v152
	s_ashr_i32 s12, s10, 2
	s_load_dwordx2 s[8:9], s[8:9], 0x88
	s_lshl_b32 s11, s36, 8
	s_andn2_b32 s12, s12, 63
	s_lshr_b32 s10, s10, 1
	s_add_i32 s12, s12, s11
	s_lshl_b32 s11, s37, 8
	s_and_b32 s10, s10, 0x60
	v_and_or_b32 v156, v152, 15, s12
	s_or_b32 s10, s10, s11
	v_lshrrev_b32_e32 v152, 1, v152
	v_and_or_b32 v152, v152, 24, s10
	v_ashrrev_i32_e32 v153, 31, v152
	s_waitcnt lgkmcnt(0)
	v_lshl_add_u64 v[152:153], v[152:153], 1, s[8:9]
	s_mov_b64 s[8:9], 0x62a4400
	v_ashrrev_i32_e32 v157, 31, v156
	v_lshl_add_u64 v[158:159], v[152:153], 0, s[8:9]
	v_lshlrev_b64 v[152:153], 11, v[156:157]
	v_lshl_add_u64 v[152:153], v[158:159], 0, v[152:153]
	s_mov_b64 s[8:9], 0x40000
	v_cvt_pk_bf16_f32 v68, v68, v69
	v_cvt_pk_bf16_f32 v69, v70, v71
	v_cvt_pk_bf16_f32 v70, v64, v65
	v_lshl_add_u64 v[64:65], v[152:153], 0, s[8:9]
	s_mov_b32 s8, 0x40000
	v_cvt_pk_bf16_f32 v60, v60, v61
	v_cvt_pk_bf16_f32 v61, v62, v63
	v_cvt_pk_bf16_f32 v62, v56, v57
	v_add_co_u32_e32 v56, vcc, s8, v152
	v_cvt_pk_bf16_f32 v48, v48, v49
	v_cvt_pk_bf16_f32 v49, v50, v51
	s_mov_b64 s[8:9], 0x48000
	s_nop 0
	v_addc_co_u32_e32 v57, vcc, 0, v153, vcc
	v_cvt_pk_bf16_f32 v50, v40, v41
	v_cvt_pk_bf16_f32 v51, v42, v43
	global_store_dwordx4 v[64:65], v[48:51], off offset:256 sc1
	v_cvt_pk_bf16_f32 v42, v44, v45
	v_cvt_pk_bf16_f32 v32, v32, v33
	v_cvt_pk_bf16_f32 v33, v34, v35
	v_cvt_pk_bf16_f32 v112, v112, v113
	v_cvt_pk_bf16_f32 v113, v114, v115
	s_nop 1
	v_lshl_add_u64 v[48:49], v[152:153], 0, s[8:9]
	s_mov_b32 s8, 0x48000
	v_add_co_u32_e32 v44, vcc, s8, v152
	s_mov_b64 s[8:9], 0x50000
	v_cvt_pk_bf16_f32 v114, v104, v105
	v_or_b32_e32 v104, 16, v156
	v_addc_co_u32_e32 v45, vcc, 0, v153, vcc
	v_cvt_pk_bf16_f32 v34, v24, v25
	v_cvt_pk_bf16_f32 v35, v26, v27
	global_store_dwordx4 v[48:49], v[32:35], off offset:256 sc1
	v_ashrrev_i32_e32 v105, 31, v104
	v_cvt_pk_bf16_f32 v96, v96, v97
	v_cvt_pk_bf16_f32 v97, v98, v99
	v_cvt_pk_bf16_f32 v98, v88, v89
	v_or_b32_e32 v88, 32, v156
	v_lshl_add_u64 v[32:33], v[152:153], 0, s[8:9]
	s_mov_b32 s8, 0x50000
	v_cvt_pk_bf16_f32 v26, v28, v29
	v_add_co_u32_e32 v28, vcc, s8, v152
	v_cvt_pk_bf16_f32 v16, v16, v17
	v_cvt_pk_bf16_f32 v17, v18, v19
	s_mov_b64 s[8:9], 0x58000
	v_lshlrev_b64 v[104:105], 11, v[104:105]
	v_ashrrev_i32_e32 v89, 31, v88
	v_cvt_pk_bf16_f32 v80, v80, v81
	v_cvt_pk_bf16_f32 v81, v82, v83
	v_cvt_pk_bf16_f32 v82, v72, v73
	v_or_b32_e32 v72, 48, v156
	v_addc_co_u32_e32 v29, vcc, 0, v153, vcc
	v_cvt_pk_bf16_f32 v18, v8, v9
	v_cvt_pk_bf16_f32 v19, v10, v11
	global_store_dwordx4 v[32:33], v[16:19], off offset:256 sc1
	v_cvt_pk_bf16_f32 v115, v106, v107
	global_store_dwordx4 v[152:153], v[112:115], off offset:256 sc1
	v_lshlrev_b64 v[88:89], 11, v[88:89]
	v_lshl_add_u64 v[16:17], v[152:153], 0, s[8:9]
	s_mov_b32 s8, 0x58000
	v_lshl_add_u64 v[112:113], v[158:159], 0, v[104:105]
	v_ashrrev_i32_e32 v73, 31, v72
	v_cvt_pk_bf16_f32 v10, v12, v13
	v_add_co_u32_e32 v12, vcc, s8, v152
	v_cvt_pk_bf16_f32 v99, v90, v91
	global_store_dwordx4 v[112:113], v[96:99], off offset:256 sc1
	v_lshlrev_b64 v[72:73], 11, v[72:73]
	v_addc_co_u32_e32 v13, vcc, 0, v153, vcc
	v_lshl_add_u64 v[96:97], v[158:159], 0, v[88:89]
	v_cvt_pk_bf16_f32 v83, v74, v75
	global_store_dwordx4 v[96:97], v[80:83], off offset:256 sc1
	s_and_b64 vcc, exec, s[4:5]
	s_mov_b32 s37, s34
	v_lshl_add_u64 v[80:81], v[158:159], 0, v[72:73]
	s_mov_b32 s36, s35
	s_mov_b64 s[10:11], s[6:7]
	s_mov_b64 s[12:13], s[2:3]
	v_cvt_pk_bf16_f32 v124, v124, v125
	v_cvt_pk_bf16_f32 v125, v126, v127
	v_cvt_pk_bf16_f32 v126, v120, v121
	v_cvt_pk_bf16_f32 v127, v122, v123
	global_store_dwordx4 v[152:153], v[124:127], off sc1
	v_cvt_pk_bf16_f32 v104, v116, v117
	v_cvt_pk_bf16_f32 v105, v118, v119
	v_cvt_pk_bf16_f32 v106, v108, v109
	v_cvt_pk_bf16_f32 v107, v110, v111
	global_store_dwordx4 v[112:113], v[104:107], off sc1
	v_cvt_pk_bf16_f32 v88, v100, v101
	v_cvt_pk_bf16_f32 v89, v102, v103
	v_cvt_pk_bf16_f32 v90, v92, v93
	v_cvt_pk_bf16_f32 v91, v94, v95
	global_store_dwordx4 v[96:97], v[88:91], off sc1
	v_cvt_pk_bf16_f32 v72, v84, v85
	v_cvt_pk_bf16_f32 v73, v86, v87
	v_cvt_pk_bf16_f32 v74, v76, v77
	v_cvt_pk_bf16_f32 v75, v78, v79
	global_store_dwordx4 v[80:81], v[72:75], off sc1
	v_cvt_pk_bf16_f32 v71, v66, v67
	global_store_dwordx4 v[80:81], v[68:71], off offset:256 sc1
	v_cvt_pk_bf16_f32 v63, v58, v59
	global_store_dwordx4 v[56:57], v[60:63], off sc1
	v_cvt_pk_bf16_f32 v40, v52, v53
	v_cvt_pk_bf16_f32 v41, v54, v55
	v_cvt_pk_bf16_f32 v43, v46, v47
	global_store_dwordx4 v[44:45], v[40:43], off sc1
	v_cvt_pk_bf16_f32 v24, v36, v37
	v_cvt_pk_bf16_f32 v25, v38, v39
	v_cvt_pk_bf16_f32 v27, v30, v31
	global_store_dwordx4 v[28:29], v[24:27], off sc1
	v_cvt_pk_bf16_f32 v8, v20, v21
	v_cvt_pk_bf16_f32 v9, v22, v23
	v_cvt_pk_bf16_f32 v11, v14, v15
	global_store_dwordx4 v[12:13], v[8:11], off sc1
	v_cvt_pk_bf16_f32 v4, v4, v5
	v_cvt_pk_bf16_f32 v5, v6, v7
	v_cvt_pk_bf16_f32 v6, v0, v1
	v_cvt_pk_bf16_f32 v7, v2, v3
	global_store_dwordx4 v[16:17], v[4:7], off offset:256 sc1
	s_cbranch_vccz .LBB0_1223
	s_waitcnt vmcnt(0)
	s_cmpk_gt_u32 s14, 0xff
	s_cbranch_scc1 .LBB0_1238
	s_barrier
